# prologue: nt hint on the read-once f32 weight / w_ada input loads
# baseline (speedup 1.0000x reference)
.LBB0_21:
	v_lshl_add_u64 v[14:15], v[4:5], 0, s[4:5]
	v_add_co_u32_e32 v150, vcc, s16, v14
	v_mov_b32_e32 v3, s36
	s_nop 0
	v_addc_co_u32_e32 v151, vcc, 0, v15, vcc
	v_add_co_u32_e32 v152, vcc, s19, v14
	ds_read_b128 v[20:23], v3
	ds_read_b128 v[24:27], v3 offset:16
	ds_read_b128 v[28:31], v3 offset:4096
	ds_read_b128 v[32:35], v3 offset:4112
	ds_read_b128 v[36:39], v3 offset:8192
	ds_read_b128 v[40:43], v3 offset:8208
	ds_read_b128 v[44:47], v3 offset:12288
	ds_read_b128 v[48:51], v3 offset:12304
	ds_read_b128 v[52:55], v3 offset:16384
	ds_read_b128 v[56:59], v3 offset:16400
	ds_read_b128 v[60:63], v3 offset:20480
	ds_read_b128 v[64:67], v3 offset:20496
	ds_read_b128 v[68:71], v3 offset:24576
	ds_read_b128 v[72:75], v3 offset:24592
	ds_read_b128 v[76:79], v3 offset:28672
	ds_read_b128 v[80:83], v3 offset:28688
	v_addc_co_u32_e32 v153, vcc, 0, v15, vcc
	v_add_co_u32_e32 v154, vcc, s20, v14
	global_load_dword v148, v[14:15], off nt
	s_nop 0
	v_addc_co_u32_e32 v155, vcc, 0, v15, vcc
	v_add_co_u32_e32 v156, vcc, s21, v14
	ds_read_b128 v[84:87], v3 offset:32
	ds_read_b128 v[88:91], v3 offset:48
	ds_read_b128 v[92:95], v3 offset:4128
	ds_read_b128 v[96:99], v3 offset:4144
	ds_read_b128 v[100:103], v3 offset:8224
	ds_read_b128 v[104:107], v3 offset:8240
	ds_read_b128 v[108:111], v3 offset:12320
	ds_read_b128 v[112:115], v3 offset:12336
	ds_read_b128 v[116:119], v3 offset:16416
	ds_read_b128 v[120:123], v3 offset:16432
	ds_read_b128 v[124:127], v3 offset:20512
	ds_read_b128 v[128:131], v3 offset:20528
	ds_read_b128 v[132:135], v3 offset:24608
	ds_read_b128 v[136:139], v3 offset:24624
	ds_read_b128 v[140:143], v3 offset:28704
	ds_read_b128 v[144:147], v3 offset:28720
	v_addc_co_u32_e32 v157, vcc, 0, v15, vcc
	v_add_co_u32_e32 v158, vcc, s22, v14
	s_waitcnt lgkmcnt(14)
	v_mov_b32_e32 v178, v20
	v_addc_co_u32_e32 v159, vcc, 0, v15, vcc
	v_add_co_u32_e32 v160, vcc, s23, v14
	v_mov_b32_e32 v179, v28
	s_nop 0
	v_addc_co_u32_e32 v161, vcc, 0, v15, vcc
	v_add_co_u32_e32 v162, vcc, s24, v14
	v_mov_b32_e32 v28, v21
	s_nop 0
	v_addc_co_u32_e32 v163, vcc, 0, v15, vcc
	v_add_co_u32_e32 v164, vcc, s25, v14
	v_mov_b32_e32 v20, v22
	s_nop 0
	v_addc_co_u32_e32 v165, vcc, 0, v15, vcc
	v_add_co_u32_e32 v166, vcc, s26, v14
	v_mov_b32_e32 v21, v30
	s_nop 0
	v_addc_co_u32_e32 v167, vcc, 0, v15, vcc
	v_add_co_u32_e32 v168, vcc, s27, v14
	v_mov_b32_e32 v30, v23
	s_nop 0
	v_addc_co_u32_e32 v169, vcc, 0, v15, vcc
	v_add_co_u32_e32 v170, vcc, s28, v14
	v_mov_b32_e32 v22, v36
	s_nop 0
	v_addc_co_u32_e32 v171, vcc, 0, v15, vcc
	v_add_co_u32_e32 v172, vcc, s29, v14
	v_mov_b32_e32 v23, v44
	s_nop 0
	v_addc_co_u32_e32 v173, vcc, 0, v15, vcc
	v_add_co_u32_e32 v174, vcc, s30, v14
	v_mov_b32_e32 v44, v37
	s_nop 0
	v_addc_co_u32_e32 v175, vcc, 0, v15, vcc
	v_add_co_u32_e32 v176, vcc, s31, v14
	v_mov_b32_e32 v36, v38
	s_nop 0
	v_addc_co_u32_e32 v177, vcc, 0, v15, vcc
	v_add_co_u32_e32 v14, vcc, s34, v14
	v_mov_b32_e32 v37, v46
	s_nop 0
	v_addc_co_u32_e32 v15, vcc, 0, v15, vcc
	global_load_dword v150, v[150:151], off nt
	s_nop 0
	global_load_dword v152, v[152:153], off nt
	s_nop 0
	global_load_dword v154, v[154:155], off nt
	s_nop 0
	global_load_dword v156, v[156:157], off nt
	s_nop 0
	global_load_dword v158, v[158:159], off nt
	s_nop 0
	global_load_dword v160, v[160:161], off nt
	s_nop 0
	global_load_dword v162, v[162:163], off nt
	s_nop 0
	global_load_dword v164, v[164:165], off nt
	s_nop 0
	global_load_dword v166, v[166:167], off nt
	s_nop 0
	global_load_dword v168, v[168:169], off nt
	s_nop 0
	global_load_dword v170, v[170:171], off nt
	s_nop 0
	global_load_dword v172, v[172:173], off nt
	s_nop 0
	global_load_dword v174, v[174:175], off nt
	s_nop 0
	global_load_dword v176, v[176:177], off nt
	s_nop 0
	global_load_dword v14, v[14:15], off nt
	v_mov_b32_e32 v46, v39
	v_mov_b32_e32 v38, v52
	v_mov_b32_e32 v39, v60
	v_mov_b32_e32 v60, v53
	v_mov_b32_e32 v52, v54
	v_mov_b32_e32 v53, v62
	v_mov_b32_e32 v62, v55
	v_mov_b32_e32 v54, v68
	v_mov_b32_e32 v55, v76
	v_mov_b32_e32 v76, v69
	v_mov_b32_e32 v68, v70
	v_mov_b32_e32 v69, v78
	v_mov_b32_e32 v78, v71
	v_mov_b32_e32 v70, v24
	v_mov_b32_e32 v71, v32
	v_mov_b32_e32 v32, v25
	s_waitcnt vmcnt(15)
	v_pk_fma_f32 v[8:9], v[148:149], v[178:179], v[8:9] op_sel_hi:[0,1,1]
	v_pk_fma_f32 v[10:11], v[148:149], v[22:23], v[10:11] op_sel_hi:[0,1,1]
	v_pk_fma_f32 v[12:13], v[148:149], v[38:39], v[12:13] op_sel_hi:[0,1,1]
	v_pk_fma_f32 v[6:7], v[148:149], v[54:55], v[6:7] op_sel_hi:[0,1,1]
	v_mov_b32_e32 v24, v26
	v_mov_b32_e32 v25, v34
	v_mov_b32_e32 v34, v27
	v_mov_b32_e32 v26, v40
	v_mov_b32_e32 v27, v48
	v_mov_b32_e32 v48, v41
	v_mov_b32_e32 v40, v42
	v_mov_b32_e32 v41, v50
	v_mov_b32_e32 v50, v43
	v_mov_b32_e32 v42, v56
	v_mov_b32_e32 v43, v64
	v_mov_b32_e32 v64, v57
	v_mov_b32_e32 v56, v58
	v_mov_b32_e32 v57, v66
	v_mov_b32_e32 v66, v59
	v_mov_b32_e32 v58, v72
	v_mov_b32_e32 v59, v80
	v_mov_b32_e32 v80, v73
	v_mov_b32_e32 v72, v74
	v_mov_b32_e32 v73, v82
	v_mov_b32_e32 v82, v75
	v_mov_b32_e32 v74, v84
	s_waitcnt lgkmcnt(13)
	v_mov_b32_e32 v75, v92
	v_mov_b32_e32 v92, v85
	v_mov_b32_e32 v84, v86
	v_mov_b32_e32 v85, v94
	v_mov_b32_e32 v94, v87
	s_waitcnt lgkmcnt(11)
	v_mov_b32_e32 v86, v100
	s_waitcnt lgkmcnt(9)
	v_mov_b32_e32 v87, v108
	v_mov_b32_e32 v108, v101
	v_mov_b32_e32 v100, v102
	v_mov_b32_e32 v101, v110
	v_mov_b32_e32 v110, v103
	s_waitcnt lgkmcnt(7)
	v_mov_b32_e32 v102, v116
	s_waitcnt lgkmcnt(5)
	v_mov_b32_e32 v103, v124
	v_mov_b32_e32 v124, v117
	v_mov_b32_e32 v116, v118
	v_mov_b32_e32 v117, v126
	v_mov_b32_e32 v126, v119
	s_waitcnt lgkmcnt(3)
	v_mov_b32_e32 v118, v132
	s_waitcnt lgkmcnt(1)
	v_mov_b32_e32 v119, v140
	v_mov_b32_e32 v140, v133
	v_mov_b32_e32 v132, v134
	v_mov_b32_e32 v133, v142
	v_mov_b32_e32 v142, v135
	s_waitcnt vmcnt(14)
	v_pk_fma_f32 v[8:9], v[150:151], v[28:29], v[8:9] op_sel_hi:[0,1,1]
	v_pk_fma_f32 v[10:11], v[150:151], v[44:45], v[10:11] op_sel_hi:[0,1,1]
	v_pk_fma_f32 v[12:13], v[150:151], v[60:61], v[12:13] op_sel_hi:[0,1,1]
	v_pk_fma_f32 v[6:7], v[150:151], v[76:77], v[6:7] op_sel_hi:[0,1,1]
	s_waitcnt vmcnt(13)
	v_pk_fma_f32 v[8:9], v[152:153], v[20:21], v[8:9] op_sel_hi:[0,1,1]
	v_pk_fma_f32 v[10:11], v[152:153], v[36:37], v[10:11] op_sel_hi:[0,1,1]
	v_pk_fma_f32 v[12:13], v[152:153], v[52:53], v[12:13] op_sel_hi:[0,1,1]
	v_pk_fma_f32 v[6:7], v[152:153], v[68:69], v[6:7] op_sel_hi:[0,1,1]
	s_waitcnt vmcnt(12)
	v_pk_fma_f32 v[8:9], v[154:155], v[30:31], v[8:9] op_sel_hi:[0,1,1]
	v_pk_fma_f32 v[10:11], v[154:155], v[46:47], v[10:11] op_sel_hi:[0,1,1]
	v_pk_fma_f32 v[12:13], v[154:155], v[62:63], v[12:13] op_sel_hi:[0,1,1]
	v_pk_fma_f32 v[6:7], v[154:155], v[78:79], v[6:7] op_sel_hi:[0,1,1]
	s_waitcnt vmcnt(11)
	v_pk_fma_f32 v[8:9], v[156:157], v[70:71], v[8:9] op_sel_hi:[0,1,1]
	v_pk_fma_f32 v[10:11], v[156:157], v[26:27], v[10:11] op_sel_hi:[0,1,1]
	v_pk_fma_f32 v[12:13], v[156:157], v[42:43], v[12:13] op_sel_hi:[0,1,1]
	v_pk_fma_f32 v[6:7], v[156:157], v[58:59], v[6:7] op_sel_hi:[0,1,1]
	s_waitcnt vmcnt(10)
	v_pk_fma_f32 v[8:9], v[158:159], v[32:33], v[8:9] op_sel_hi:[0,1,1]
	v_pk_fma_f32 v[10:11], v[158:159], v[48:49], v[10:11] op_sel_hi:[0,1,1]
	v_pk_fma_f32 v[12:13], v[158:159], v[64:65], v[12:13] op_sel_hi:[0,1,1]
	v_pk_fma_f32 v[6:7], v[158:159], v[80:81], v[6:7] op_sel_hi:[0,1,1]
	s_waitcnt vmcnt(9)
	v_pk_fma_f32 v[8:9], v[160:161], v[24:25], v[8:9] op_sel_hi:[0,1,1]
	v_pk_fma_f32 v[10:11], v[160:161], v[40:41], v[10:11] op_sel_hi:[0,1,1]
	v_pk_fma_f32 v[12:13], v[160:161], v[56:57], v[12:13] op_sel_hi:[0,1,1]
	v_pk_fma_f32 v[6:7], v[160:161], v[72:73], v[6:7] op_sel_hi:[0,1,1]
	s_waitcnt vmcnt(8)
	v_pk_fma_f32 v[8:9], v[162:163], v[34:35], v[8:9] op_sel_hi:[0,1,1]
	v_pk_fma_f32 v[10:11], v[162:163], v[50:51], v[10:11] op_sel_hi:[0,1,1]
	v_pk_fma_f32 v[12:13], v[162:163], v[66:67], v[12:13] op_sel_hi:[0,1,1]
	v_pk_fma_f32 v[6:7], v[162:163], v[82:83], v[6:7] op_sel_hi:[0,1,1]
	s_waitcnt vmcnt(7)
	v_pk_fma_f32 v[8:9], v[164:165], v[74:75], v[8:9] op_sel_hi:[0,1,1]
	v_pk_fma_f32 v[10:11], v[164:165], v[86:87], v[10:11] op_sel_hi:[0,1,1]
	v_pk_fma_f32 v[12:13], v[164:165], v[102:103], v[12:13] op_sel_hi:[0,1,1]
	v_pk_fma_f32 v[6:7], v[164:165], v[118:119], v[6:7] op_sel_hi:[0,1,1]
	s_waitcnt vmcnt(6)
	v_pk_fma_f32 v[8:9], v[166:167], v[92:93], v[8:9] op_sel_hi:[0,1,1]
	v_pk_fma_f32 v[10:11], v[166:167], v[108:109], v[10:11] op_sel_hi:[0,1,1]
	v_pk_fma_f32 v[12:13], v[166:167], v[124:125], v[12:13] op_sel_hi:[0,1,1]
	v_pk_fma_f32 v[6:7], v[166:167], v[140:141], v[6:7] op_sel_hi:[0,1,1]
	s_waitcnt vmcnt(5)
	v_pk_fma_f32 v[8:9], v[168:169], v[84:85], v[8:9] op_sel_hi:[0,1,1]
	v_pk_fma_f32 v[10:11], v[168:169], v[100:101], v[10:11] op_sel_hi:[0,1,1]
	v_pk_fma_f32 v[12:13], v[168:169], v[116:117], v[12:13] op_sel_hi:[0,1,1]
	v_pk_fma_f32 v[6:7], v[168:169], v[132:133], v[6:7] op_sel_hi:[0,1,1]
	v_mov_b32_e32 v134, v88
	v_mov_b32_e32 v135, v96
	v_mov_b32_e32 v96, v89
	v_mov_b32_e32 v88, v90
	v_mov_b32_e32 v89, v98
	v_mov_b32_e32 v98, v91
	v_mov_b32_e32 v90, v104
	v_mov_b32_e32 v91, v112
	v_mov_b32_e32 v112, v105
	v_mov_b32_e32 v104, v106
	v_mov_b32_e32 v105, v114
	v_mov_b32_e32 v114, v107
	v_mov_b32_e32 v106, v120
	v_mov_b32_e32 v107, v128
	v_mov_b32_e32 v128, v121
	v_mov_b32_e32 v120, v122
	v_mov_b32_e32 v121, v130
	v_mov_b32_e32 v130, v123
	v_mov_b32_e32 v122, v136
	s_waitcnt lgkmcnt(0)
	v_mov_b32_e32 v123, v144
	s_waitcnt vmcnt(4)
	v_pk_fma_f32 v[8:9], v[170:171], v[94:95], v[8:9] op_sel_hi:[0,1,1]
	v_pk_fma_f32 v[10:11], v[170:171], v[110:111], v[10:11] op_sel_hi:[0,1,1]
	v_pk_fma_f32 v[12:13], v[170:171], v[126:127], v[12:13] op_sel_hi:[0,1,1]
	v_pk_fma_f32 v[6:7], v[170:171], v[142:143], v[6:7] op_sel_hi:[0,1,1]
	v_mov_b32_e32 v144, v137
	s_waitcnt vmcnt(3)
	v_pk_fma_f32 v[8:9], v[172:173], v[134:135], v[8:9] op_sel_hi:[0,1,1]
	v_pk_fma_f32 v[10:11], v[172:173], v[90:91], v[10:11] op_sel_hi:[0,1,1]
	v_pk_fma_f32 v[12:13], v[172:173], v[106:107], v[12:13] op_sel_hi:[0,1,1]
	v_pk_fma_f32 v[6:7], v[172:173], v[122:123], v[6:7] op_sel_hi:[0,1,1]
	s_add_u32 s4, s4, 0x90000
	v_mov_b32_e32 v136, v138
	v_mov_b32_e32 v137, v146
	s_waitcnt vmcnt(2)
	v_pk_fma_f32 v[8:9], v[174:175], v[96:97], v[8:9] op_sel_hi:[0,1,1]
	v_pk_fma_f32 v[10:11], v[174:175], v[112:113], v[10:11] op_sel_hi:[0,1,1]
	v_pk_fma_f32 v[12:13], v[174:175], v[128:129], v[12:13] op_sel_hi:[0,1,1]
	v_pk_fma_f32 v[6:7], v[174:175], v[144:145], v[6:7] op_sel_hi:[0,1,1]
	s_addc_u32 s5, s5, 0
	s_add_i32 s36, s36, 64
	v_mov_b32_e32 v146, v139
	s_waitcnt vmcnt(1)
	v_pk_fma_f32 v[8:9], v[176:177], v[88:89], v[8:9] op_sel_hi:[0,1,1]
	v_pk_fma_f32 v[10:11], v[176:177], v[104:105], v[10:11] op_sel_hi:[0,1,1]
	v_pk_fma_f32 v[12:13], v[176:177], v[120:121], v[12:13] op_sel_hi:[0,1,1]
	v_pk_fma_f32 v[6:7], v[176:177], v[136:137], v[6:7] op_sel_hi:[0,1,1]
	s_cmp_eq_u32 s4, 0x480000
	s_waitcnt vmcnt(0)
	v_pk_fma_f32 v[8:9], v[14:15], v[98:99], v[8:9] op_sel_hi:[0,1,1]
	v_pk_fma_f32 v[10:11], v[14:15], v[114:115], v[10:11] op_sel_hi:[0,1,1]
	v_pk_fma_f32 v[12:13], v[14:15], v[130:131], v[12:13] op_sel_hi:[0,1,1]
	v_pk_fma_f32 v[6:7], v[14:15], v[146:147], v[6:7] op_sel_hi:[0,1,1]
	s_cbranch_scc0 .LBB0_21
	v_lshl_or_b32 v4, s35, 6, v16
	v_ashrrev_i32_e32 v5, 31, v4
	v_add_u32_e32 v3, s9, v1
	ds_write2st64_b32 v3, v8, v9 offset0:128 offset1:129
	ds_write2st64_b32 v3, v10, v11 offset0:130 offset1:131
	ds_write2st64_b32 v3, v12, v13 offset0:132 offset1:133
	ds_write2st64_b32 v3, v6, v7 offset0:134 offset1:135
	v_lshl_add_u64 v[6:7], v[4:5], 2, s[70:71]
	s_waitcnt lgkmcnt(0)
	s_barrier
	global_load_dword v3, v[6:7], off nt
	ds_read2st64_b32 v[6:7], v17 offset0:128 offset1:136
	ds_read2st64_b32 v[8:9], v17 offset0:144 offset1:152
	ds_read2st64_b32 v[10:11], v17 offset0:160 offset1:168
	ds_read2st64_b32 v[12:13], v17 offset0:176 offset1:184
	v_add_u32_e32 v4, v4, v18
	s_waitcnt lgkmcnt(3)
	v_add_f32_e32 v6, 0, v6
	v_add_f32_e32 v6, v6, v7
	s_waitcnt lgkmcnt(2)
	v_add_f32_e32 v6, v6, v8
	v_add_f32_e32 v6, v6, v9
	s_waitcnt lgkmcnt(1)
	v_add_f32_e32 v6, v6, v10
	v_add_f32_e32 v6, v6, v11
	s_waitcnt lgkmcnt(0)
	v_add_f32_e32 v6, v6, v12
	s_add_i32 s35, s35, s17
	v_ashrrev_i32_e32 v5, 31, v4
	v_add_f32_e32 v6, v6, v13
	s_cmpk_gt_i32 s35, 0x8f
	v_lshl_add_u64 v[4:5], v[4:5], 2, s[2:3]
	v_add_u32_e32 v2, s18, v2
	s_waitcnt vmcnt(0)
	v_add_f32_e32 v3, v6, v3
	global_store_dword v[4:5], v3, off
	s_barrier
	s_cbranch_scc0 .LBB0_20

.LBB0_26:
	global_load_dword v7, v[2:3], off nt
	global_load_dword v8, v[2:3], off offset:-4096 nt
	v_add_u32_e32 v6, 0x200, v6
	v_cmp_lt_i32_e32 vcc, s20, v6
	s_or_b64 s[4:5], vcc, s[4:5]
	v_lshl_add_u64 v[2:3], v[2:3], 0, s[8:9]
	s_waitcnt vmcnt(0)
	v_sub_f32_e32 v7, v7, v8
	v_mul_f32_e32 v8, 0x3fb8aa3b, v7
	v_fma_f32 v9, v7, s16, -v8
	v_rndne_f32_e32 v10, v8
	v_fmac_f32_e32 v9, 0x32a5705f, v7
	v_sub_f32_e32 v8, v8, v10
	v_add_f32_e32 v8, v8, v9
	v_cvt_i32_f32_e32 v10, v10
	v_exp_f32_e32 v8, v8
	v_cmp_ngt_f32_e32 vcc, s18, v7
	v_ldexp_f32 v8, v8, v10
	s_nop 0
	v_cndmask_b32_e32 v8, 0, v8, vcc
	v_cmp_nlt_f32_e32 vcc, s19, v7
	s_nop 1
	v_cndmask_b32_e32 v7, v1, v8, vcc
	v_add_f32_e32 v7, 1.0, v7
	v_div_scale_f32 v8, s[22:23], v7, v7, 1.0
	v_rcp_f32_e32 v9, v8
	v_div_scale_f32 v10, vcc, 1.0, v7, 1.0
	v_fma_f32 v11, -v8, v9, 1.0
	v_fmac_f32_e32 v9, v11, v9
	v_mul_f32_e32 v11, v10, v9
	v_fma_f32 v12, -v8, v11, v10
	v_fmac_f32_e32 v11, v12, v9
	v_fma_f32 v8, -v8, v11, v10
	v_div_fmas_f32 v8, v8, v9, v11
	v_div_fixup_f32 v7, v8, v7, 1.0
	global_store_dword v[4:5], v7, off
	v_lshl_add_u64 v[4:5], v[4:5], 0, s[8:9]
	s_andn2_b64 exec, exec, s[4:5]
	s_cbranch_execnz .LBB0_26

.LBB0_31:
	s_cmpk_gt_i32 s4, 0x11ff
	s_mov_b64 s[2:3], -1
	s_cbranch_scc0 .LBB0_57
	s_cmpk_gt_u32 s4, 0x1cff
	s_cbranch_scc0 .LBB0_54
	s_cmpk_gt_u32 s4, 0x27ff
	s_cbranch_scc0 .LBB0_51
	s_and_b32 s53, s8, 0x3e0
	s_cmpk_gt_u32 s4, 0x2d7f
	s_cbranch_scc0 .LBB0_48
	s_cmpk_gt_u32 s4, 0x32ff
	s_cbranch_scc0 .LBB0_45
	s_cmpk_gt_u32 s4, 0x34ff
	s_cbranch_scc0 .LBB0_42
	s_cmpk_gt_u32 s4, 0x36ff
	s_cbranch_scc0 .LBB0_39
	s_add_i32 s0, s16, 0xffffe200
	s_and_b32 s2, s0, 0x1ffc0
	v_or_b32_e32 v0, s2, v34
	s_lshl_b32 s0, s53, 2
	v_lshl_add_u64 v[48:49], v[18:19], 0, s[0:1]
	v_lshlrev_b32_e32 v0, 12, v0
	v_lshl_add_u64 v[48:49], v[48:49], 0, v[0:1]
	v_add_co_u32_e32 v50, vcc, 0x2000, v48
	s_lshl_b32 s0, s2, 1
	s_nop 0
	v_addc_co_u32_e32 v51, vcc, 0, v49, vcc
	v_add_co_u32_e32 v52, vcc, 0x4000, v48
	s_mov_b64 s[2:3], 0
	s_nop 0
	v_addc_co_u32_e32 v53, vcc, 0, v49, vcc
	v_add_co_u32_e32 v54, vcc, 0x6000, v48
	s_nop 1
	v_addc_co_u32_e32 v55, vcc, 0, v49, vcc
	v_add_co_u32_e32 v56, vcc, 0x8000, v48
	s_nop 1
	v_addc_co_u32_e32 v57, vcc, 0, v49, vcc
	v_add_co_u32_e32 v58, vcc, 0xa000, v48
	s_nop 1
	v_addc_co_u32_e32 v59, vcc, 0, v49, vcc
	v_add_co_u32_e32 v60, vcc, 0xc000, v48
	s_nop 1
	v_addc_co_u32_e32 v61, vcc, 0, v49, vcc
	v_add_co_u32_e32 v62, vcc, 0xe000, v48
	s_nop 1
	v_addc_co_u32_e32 v63, vcc, 0, v49, vcc
	global_load_dword v0, v[48:49], off nt
	global_load_dword v66, v[50:51], off nt
	global_load_dword v67, v[52:53], off nt
	global_load_dword v68, v[54:55], off nt
	global_load_dword v69, v[56:57], off nt
	global_load_dword v70, v[58:59], off nt
	global_load_dword v71, v[60:61], off nt
	global_load_dword v72, v[62:63], off nt
	v_add_co_u32_e32 v50, vcc, 0x10000, v48
	s_nop 1
	v_addc_co_u32_e32 v51, vcc, 0, v49, vcc
	v_add_co_u32_e32 v52, vcc, 0x12000, v48
	s_nop 1
	v_addc_co_u32_e32 v53, vcc, 0, v49, vcc
	v_add_co_u32_e32 v54, vcc, 0x14000, v48
	s_nop 1
	v_addc_co_u32_e32 v55, vcc, 0, v49, vcc
	v_add_co_u32_e32 v56, vcc, 0x16000, v48
	s_nop 1
	v_addc_co_u32_e32 v57, vcc, 0, v49, vcc
	v_add_co_u32_e32 v58, vcc, 0x18000, v48
	s_nop 1
	v_addc_co_u32_e32 v59, vcc, 0, v49, vcc
	v_add_co_u32_e32 v60, vcc, 0x1a000, v48
	s_nop 1
	v_addc_co_u32_e32 v61, vcc, 0, v49, vcc
	v_add_co_u32_e32 v62, vcc, 0x1c000, v48
	s_nop 1
	v_addc_co_u32_e32 v63, vcc, 0, v49, vcc
	v_add_co_u32_e32 v64, vcc, 0x1e000, v48
	s_nop 1
	v_addc_co_u32_e32 v65, vcc, 0, v49, vcc
	global_load_dword v73, v[50:51], off nt
	global_load_dword v74, v[52:53], off nt
	global_load_dword v75, v[54:55], off nt
	global_load_dword v76, v[56:57], off nt
	global_load_dword v77, v[58:59], off nt
	global_load_dword v78, v[60:61], off nt
	global_load_dword v79, v[62:63], off nt
	global_load_dword v80, v[64:65], off nt
	v_add_co_u32_e32 v50, vcc, 0x20000, v48
	s_nop 1
	v_addc_co_u32_e32 v51, vcc, 0, v49, vcc
	v_add_co_u32_e32 v52, vcc, 0x22000, v48
	s_nop 1
	v_addc_co_u32_e32 v53, vcc, 0, v49, vcc
	v_add_co_u32_e32 v54, vcc, 0x24000, v48
	s_nop 1
	v_addc_co_u32_e32 v55, vcc, 0, v49, vcc
	v_add_co_u32_e32 v56, vcc, 0x26000, v48
	s_nop 1
	v_addc_co_u32_e32 v57, vcc, 0, v49, vcc
	v_add_co_u32_e32 v58, vcc, 0x28000, v48
	s_nop 1
	v_addc_co_u32_e32 v59, vcc, 0, v49, vcc
	v_add_co_u32_e32 v60, vcc, 0x2a000, v48
	s_nop 1
	v_addc_co_u32_e32 v61, vcc, 0, v49, vcc
	v_add_co_u32_e32 v62, vcc, 0x2c000, v48
	s_nop 1
	v_addc_co_u32_e32 v63, vcc, 0, v49, vcc
	v_add_co_u32_e32 v64, vcc, 0x2e000, v48
	s_nop 1
	v_addc_co_u32_e32 v65, vcc, 0, v49, vcc
	global_load_dword v81, v[50:51], off nt
	global_load_dword v82, v[52:53], off nt
	global_load_dword v83, v[54:55], off nt
	global_load_dword v84, v[56:57], off nt
	global_load_dword v85, v[58:59], off nt
	global_load_dword v86, v[60:61], off nt
	global_load_dword v87, v[62:63], off nt
	s_nop 0
	global_load_dword v64, v[64:65], off nt
	v_add_co_u32_e32 v50, vcc, 0x30000, v48
	s_nop 1
	v_addc_co_u32_e32 v51, vcc, 0, v49, vcc
	v_add_co_u32_e32 v52, vcc, 0x32000, v48
	s_nop 1
	v_addc_co_u32_e32 v53, vcc, 0, v49, vcc
	v_add_co_u32_e32 v54, vcc, 0x34000, v48
	s_nop 1
	v_addc_co_u32_e32 v55, vcc, 0, v49, vcc
	v_add_co_u32_e32 v56, vcc, 0x36000, v48
	s_nop 1
	v_addc_co_u32_e32 v57, vcc, 0, v49, vcc
	v_add_co_u32_e32 v58, vcc, 0x38000, v48
	s_nop 1
	v_addc_co_u32_e32 v59, vcc, 0, v49, vcc
	v_add_co_u32_e32 v60, vcc, 0x3a000, v48
	s_nop 1
	v_addc_co_u32_e32 v61, vcc, 0, v49, vcc
	v_add_co_u32_e32 v62, vcc, 0x3c000, v48
	s_nop 1
	v_addc_co_u32_e32 v63, vcc, 0, v49, vcc
	v_add_co_u32_e32 v48, vcc, 0x3e000, v48
	s_nop 1
	v_addc_co_u32_e32 v49, vcc, 0, v49, vcc
	global_load_dword v50, v[50:51], off nt
	s_nop 0
	global_load_dword v51, v[52:53], off nt
	s_nop 0
	global_load_dword v52, v[54:55], off nt
	global_load_dword v53, v[56:57], off nt
	s_nop 0
	global_load_dword v54, v[58:59], off nt
	global_load_dword v55, v[60:61], off nt
	global_load_dword v56, v[62:63], off nt
	s_nop 0
	global_load_dword v48, v[48:49], off nt
	s_waitcnt vmcnt(30)
	ds_write2_b32 v39, v0, v66 offset1:66
	s_waitcnt vmcnt(28)
	ds_write2_b32 v39, v67, v68 offset0:132 offset1:198
	s_waitcnt vmcnt(26)
	ds_write2_b32 v40, v69, v70 offset0:8 offset1:74
	s_waitcnt vmcnt(24)
	ds_write2_b32 v40, v71, v72 offset0:140 offset1:206
	s_waitcnt vmcnt(22)
	ds_write2_b32 v41, v73, v74 offset0:16 offset1:82
	s_waitcnt vmcnt(20)
	ds_write2_b32 v41, v75, v76 offset0:148 offset1:214
	s_waitcnt vmcnt(18)
	ds_write2_b32 v42, v77, v78 offset0:24 offset1:90
	s_waitcnt vmcnt(16)
	ds_write2_b32 v42, v79, v80 offset0:156 offset1:222
	s_waitcnt vmcnt(14)
	ds_write2_b32 v43, v81, v82 offset0:32 offset1:98
	s_waitcnt vmcnt(12)
	ds_write2_b32 v43, v83, v84 offset0:164 offset1:230
	s_waitcnt vmcnt(10)
	ds_write2_b32 v44, v85, v86 offset0:40 offset1:106
	s_waitcnt vmcnt(8)
	ds_write2_b32 v44, v87, v64 offset0:172 offset1:238
	s_waitcnt vmcnt(6)
	ds_write2_b32 v45, v50, v51 offset0:48 offset1:114
	s_waitcnt vmcnt(4)
	ds_write2_b32 v45, v52, v53 offset0:180 offset1:246
	s_waitcnt vmcnt(2)
	ds_write2_b32 v46, v54, v55 offset0:56 offset1:122
	s_waitcnt vmcnt(0)
	ds_write2_b32 v46, v56, v48 offset0:188 offset1:254
	s_waitcnt lgkmcnt(0)
	ds_read2_b32 v[52:53], v47 offset0:33 offset1:41
	ds_read2_b32 v[54:55], v47 offset1:8
	ds_read2_b32 v[56:57], v47 offset0:66 offset1:74
	ds_read2_b32 v[58:59], v47 offset0:99 offset1:107
	ds_read2_b32 v[60:61], v47 offset0:132 offset1:140
	ds_read2_b32 v[62:63], v47 offset0:165 offset1:173
	ds_read2_b32 v[64:65], v47 offset0:198 offset1:206
	ds_read2_b32 v[66:67], v47 offset0:231 offset1:239
	v_or_b32_e32 v0, s53, v35
	v_lshl_add_u64 v[68:69], v[2:3], 0, s[0:1]
	v_lshlrev_b32_e32 v0, 11, v0
	s_waitcnt lgkmcnt(6)
	v_cvt_pk_bf16_f32 v48, v54, v52
	s_waitcnt lgkmcnt(4)
	v_cvt_pk_bf16_f32 v49, v56, v58
	s_waitcnt lgkmcnt(2)
	v_cvt_pk_bf16_f32 v50, v60, v62
	s_waitcnt lgkmcnt(0)
	v_cvt_pk_bf16_f32 v51, v64, v66
	v_lshl_add_u64 v[70:71], v[68:69], 0, v[0:1]
	global_store_dwordx4 v[70:71], v[48:51], off
	v_or_b32_e32 v0, s53, v36
	v_lshlrev_b32_e32 v0, 11, v0
	v_cvt_pk_bf16_f32 v48, v55, v53
	v_cvt_pk_bf16_f32 v49, v57, v59
	v_cvt_pk_bf16_f32 v50, v61, v63
	v_cvt_pk_bf16_f32 v51, v65, v67
	ds_read2_b32 v[54:55], v47 offset0:49 offset1:57
	ds_read2_b32 v[56:57], v47 offset0:16 offset1:24
	ds_read2_b32 v[58:59], v47 offset0:82 offset1:90
	ds_read2_b32 v[60:61], v47 offset0:115 offset1:123
	ds_read2_b32 v[62:63], v47 offset0:148 offset1:156
	ds_read2_b32 v[64:65], v47 offset0:181 offset1:189
	ds_read2_b32 v[66:67], v47 offset0:214 offset1:222
	ds_read2_b32 v[70:71], v47 offset0:247 offset1:255
	v_lshl_add_u64 v[52:53], v[68:69], 0, v[0:1]
	v_or_b32_e32 v0, s53, v37
	v_lshlrev_b32_e32 v0, 11, v0
	global_store_dwordx4 v[52:53], v[48:51], off
	v_lshl_add_u64 v[52:53], v[68:69], 0, v[0:1]
	v_or_b32_e32 v0, s53, v38
	s_waitcnt lgkmcnt(6)
	v_cvt_pk_bf16_f32 v48, v56, v54
	s_waitcnt lgkmcnt(4)
	v_cvt_pk_bf16_f32 v49, v58, v60
	s_waitcnt lgkmcnt(2)
	v_cvt_pk_bf16_f32 v50, v62, v64
	s_waitcnt lgkmcnt(0)
	v_cvt_pk_bf16_f32 v51, v66, v70
	v_lshlrev_b32_e32 v0, 11, v0
	global_store_dwordx4 v[52:53], v[48:51], off
	v_lshl_add_u64 v[52:53], v[68:69], 0, v[0:1]
	s_nop 0
	v_cvt_pk_bf16_f32 v48, v57, v55
	v_cvt_pk_bf16_f32 v49, v59, v61
	v_cvt_pk_bf16_f32 v50, v63, v65
	v_cvt_pk_bf16_f32 v51, v67, v71
	global_store_dwordx4 v[52:53], v[48:51], off
	s_waitcnt lgkmcnt(0)
.LBB0_39:
	s_andn2_b64 vcc, exec, s[2:3]
	s_cbranch_vccnz .LBB0_41
	s_add_i32 s0, s16, 0xffffe600
	s_and_b32 s2, s0, 0x1ffc0
	v_or_b32_e32 v0, s2, v34
	s_lshl_b32 s0, s53, 2
	v_lshl_add_u64 v[48:49], v[20:21], 0, s[0:1]
	v_lshlrev_b32_e32 v0, 12, v0
	v_lshl_add_u64 v[48:49], v[48:49], 0, v[0:1]
	v_add_co_u32_e32 v50, vcc, 0x2000, v48
	s_lshl_b32 s0, s2, 1
	s_nop 0
	v_addc_co_u32_e32 v51, vcc, 0, v49, vcc
	v_add_co_u32_e32 v52, vcc, 0x4000, v48
	s_nop 1
	v_addc_co_u32_e32 v53, vcc, 0, v49, vcc
	v_add_co_u32_e32 v54, vcc, 0x6000, v48
	s_nop 1
	v_addc_co_u32_e32 v55, vcc, 0, v49, vcc
	v_add_co_u32_e32 v56, vcc, 0x8000, v48
	s_nop 1
	v_addc_co_u32_e32 v57, vcc, 0, v49, vcc
	v_add_co_u32_e32 v58, vcc, 0xa000, v48
	s_nop 1
	v_addc_co_u32_e32 v59, vcc, 0, v49, vcc
	v_add_co_u32_e32 v60, vcc, 0xc000, v48
	s_nop 1
	v_addc_co_u32_e32 v61, vcc, 0, v49, vcc
	v_add_co_u32_e32 v62, vcc, 0xe000, v48
	s_nop 1
	v_addc_co_u32_e32 v63, vcc, 0, v49, vcc
	global_load_dword v0, v[48:49], off nt
	global_load_dword v66, v[50:51], off nt
	global_load_dword v67, v[52:53], off nt
	global_load_dword v68, v[54:55], off nt
	global_load_dword v69, v[56:57], off nt
	global_load_dword v70, v[58:59], off nt
	global_load_dword v71, v[60:61], off nt
	global_load_dword v72, v[62:63], off nt
	v_add_co_u32_e32 v50, vcc, 0x10000, v48
	s_nop 1
	v_addc_co_u32_e32 v51, vcc, 0, v49, vcc
	v_add_co_u32_e32 v52, vcc, 0x12000, v48
	s_nop 1
	v_addc_co_u32_e32 v53, vcc, 0, v49, vcc
	v_add_co_u32_e32 v54, vcc, 0x14000, v48
	s_nop 1
	v_addc_co_u32_e32 v55, vcc, 0, v49, vcc
	v_add_co_u32_e32 v56, vcc, 0x16000, v48
	s_nop 1
	v_addc_co_u32_e32 v57, vcc, 0, v49, vcc
	v_add_co_u32_e32 v58, vcc, 0x18000, v48
	s_nop 1
	v_addc_co_u32_e32 v59, vcc, 0, v49, vcc
	v_add_co_u32_e32 v60, vcc, 0x1a000, v48
	s_nop 1
	v_addc_co_u32_e32 v61, vcc, 0, v49, vcc
	v_add_co_u32_e32 v62, vcc, 0x1c000, v48
	s_nop 1
	v_addc_co_u32_e32 v63, vcc, 0, v49, vcc
	v_add_co_u32_e32 v64, vcc, 0x1e000, v48
	s_nop 1
	v_addc_co_u32_e32 v65, vcc, 0, v49, vcc
	global_load_dword v73, v[50:51], off nt
	global_load_dword v74, v[52:53], off nt
	global_load_dword v75, v[54:55], off nt
	global_load_dword v76, v[56:57], off nt
	global_load_dword v77, v[58:59], off nt
	global_load_dword v78, v[60:61], off nt
	global_load_dword v79, v[62:63], off nt
	global_load_dword v80, v[64:65], off nt
	v_add_co_u32_e32 v50, vcc, 0x20000, v48
	s_nop 1
	v_addc_co_u32_e32 v51, vcc, 0, v49, vcc
	v_add_co_u32_e32 v52, vcc, 0x22000, v48
	s_nop 1
	v_addc_co_u32_e32 v53, vcc, 0, v49, vcc
	v_add_co_u32_e32 v54, vcc, 0x24000, v48
	s_nop 1
	v_addc_co_u32_e32 v55, vcc, 0, v49, vcc
	v_add_co_u32_e32 v56, vcc, 0x26000, v48
	s_nop 1
	v_addc_co_u32_e32 v57, vcc, 0, v49, vcc
	v_add_co_u32_e32 v58, vcc, 0x28000, v48
	s_nop 1
	v_addc_co_u32_e32 v59, vcc, 0, v49, vcc
	v_add_co_u32_e32 v60, vcc, 0x2a000, v48
	s_nop 1
	v_addc_co_u32_e32 v61, vcc, 0, v49, vcc
	v_add_co_u32_e32 v62, vcc, 0x2c000, v48
	s_nop 1
	v_addc_co_u32_e32 v63, vcc, 0, v49, vcc
	v_add_co_u32_e32 v64, vcc, 0x2e000, v48
	s_nop 1
	v_addc_co_u32_e32 v65, vcc, 0, v49, vcc
	global_load_dword v81, v[50:51], off nt
	global_load_dword v82, v[52:53], off nt
	global_load_dword v83, v[54:55], off nt
	global_load_dword v84, v[56:57], off nt
	global_load_dword v85, v[58:59], off nt
	global_load_dword v86, v[60:61], off nt
	global_load_dword v87, v[62:63], off nt
	s_nop 0
	global_load_dword v64, v[64:65], off nt
	v_add_co_u32_e32 v50, vcc, 0x30000, v48
	s_nop 1
	v_addc_co_u32_e32 v51, vcc, 0, v49, vcc
	v_add_co_u32_e32 v52, vcc, 0x32000, v48
	s_nop 1
	v_addc_co_u32_e32 v53, vcc, 0, v49, vcc
	v_add_co_u32_e32 v54, vcc, 0x34000, v48
	s_nop 1
	v_addc_co_u32_e32 v55, vcc, 0, v49, vcc
	v_add_co_u32_e32 v56, vcc, 0x36000, v48
	s_nop 1
	v_addc_co_u32_e32 v57, vcc, 0, v49, vcc
	v_add_co_u32_e32 v58, vcc, 0x38000, v48
	s_nop 1
	v_addc_co_u32_e32 v59, vcc, 0, v49, vcc
	v_add_co_u32_e32 v60, vcc, 0x3a000, v48
	s_nop 1
	v_addc_co_u32_e32 v61, vcc, 0, v49, vcc
	v_add_co_u32_e32 v62, vcc, 0x3c000, v48
	s_nop 1
	v_addc_co_u32_e32 v63, vcc, 0, v49, vcc
	v_add_co_u32_e32 v48, vcc, 0x3e000, v48
	s_nop 1
	v_addc_co_u32_e32 v49, vcc, 0, v49, vcc
	global_load_dword v50, v[50:51], off nt
	s_nop 0
	global_load_dword v51, v[52:53], off nt
	s_nop 0
	global_load_dword v52, v[54:55], off nt
	global_load_dword v53, v[56:57], off nt
	s_nop 0
	global_load_dword v54, v[58:59], off nt
	global_load_dword v55, v[60:61], off nt
	global_load_dword v56, v[62:63], off nt
	s_nop 0
	global_load_dword v48, v[48:49], off nt
	s_waitcnt vmcnt(30)
	ds_write2_b32 v39, v0, v66 offset1:66
	s_waitcnt vmcnt(28)
	ds_write2_b32 v39, v67, v68 offset0:132 offset1:198
	s_waitcnt vmcnt(26)
	ds_write2_b32 v40, v69, v70 offset0:8 offset1:74
	s_waitcnt vmcnt(24)
	ds_write2_b32 v40, v71, v72 offset0:140 offset1:206
	s_waitcnt vmcnt(22)
	ds_write2_b32 v41, v73, v74 offset0:16 offset1:82
	s_waitcnt vmcnt(20)
	ds_write2_b32 v41, v75, v76 offset0:148 offset1:214
	s_waitcnt vmcnt(18)
	ds_write2_b32 v42, v77, v78 offset0:24 offset1:90
	s_waitcnt vmcnt(16)
	ds_write2_b32 v42, v79, v80 offset0:156 offset1:222
	s_waitcnt vmcnt(14)
	ds_write2_b32 v43, v81, v82 offset0:32 offset1:98
	s_waitcnt vmcnt(12)
	ds_write2_b32 v43, v83, v84 offset0:164 offset1:230
	s_waitcnt vmcnt(10)
	ds_write2_b32 v44, v85, v86 offset0:40 offset1:106
	s_waitcnt vmcnt(8)
	ds_write2_b32 v44, v87, v64 offset0:172 offset1:238
	s_waitcnt vmcnt(6)
	ds_write2_b32 v45, v50, v51 offset0:48 offset1:114
	s_waitcnt vmcnt(4)
	ds_write2_b32 v45, v52, v53 offset0:180 offset1:246
	s_waitcnt vmcnt(2)
	ds_write2_b32 v46, v54, v55 offset0:56 offset1:122
	s_waitcnt vmcnt(0)
	ds_write2_b32 v46, v56, v48 offset0:188 offset1:254
	s_waitcnt lgkmcnt(0)
	ds_read2_b32 v[52:53], v47 offset0:33 offset1:41
	ds_read2_b32 v[54:55], v47 offset1:8
	ds_read2_b32 v[56:57], v47 offset0:66 offset1:74
	ds_read2_b32 v[58:59], v47 offset0:99 offset1:107
	ds_read2_b32 v[60:61], v47 offset0:132 offset1:140
	ds_read2_b32 v[62:63], v47 offset0:165 offset1:173
	ds_read2_b32 v[64:65], v47 offset0:198 offset1:206
	ds_read2_b32 v[66:67], v47 offset0:231 offset1:239
	v_or_b32_e32 v0, s53, v35
	v_lshl_add_u64 v[68:69], v[4:5], 0, s[0:1]
	v_lshlrev_b32_e32 v0, 11, v0
	s_waitcnt lgkmcnt(6)
	v_cvt_pk_bf16_f32 v48, v54, v52
	s_waitcnt lgkmcnt(4)
	v_cvt_pk_bf16_f32 v49, v56, v58
	s_waitcnt lgkmcnt(2)
	v_cvt_pk_bf16_f32 v50, v60, v62
	s_waitcnt lgkmcnt(0)
	v_cvt_pk_bf16_f32 v51, v64, v66
	v_lshl_add_u64 v[70:71], v[68:69], 0, v[0:1]
	global_store_dwordx4 v[70:71], v[48:51], off
	v_or_b32_e32 v0, s53, v36
	v_lshlrev_b32_e32 v0, 11, v0
	v_cvt_pk_bf16_f32 v48, v55, v53
	v_cvt_pk_bf16_f32 v49, v57, v59
	v_cvt_pk_bf16_f32 v50, v61, v63
	v_cvt_pk_bf16_f32 v51, v65, v67
	ds_read2_b32 v[54:55], v47 offset0:49 offset1:57
	ds_read2_b32 v[56:57], v47 offset0:16 offset1:24
	ds_read2_b32 v[58:59], v47 offset0:82 offset1:90
	ds_read2_b32 v[60:61], v47 offset0:115 offset1:123
	ds_read2_b32 v[62:63], v47 offset0:148 offset1:156
	ds_read2_b32 v[64:65], v47 offset0:181 offset1:189
	ds_read2_b32 v[66:67], v47 offset0:214 offset1:222
	ds_read2_b32 v[70:71], v47 offset0:247 offset1:255
	v_lshl_add_u64 v[52:53], v[68:69], 0, v[0:1]
	v_or_b32_e32 v0, s53, v37
	v_lshlrev_b32_e32 v0, 11, v0
	global_store_dwordx4 v[52:53], v[48:51], off
	v_lshl_add_u64 v[52:53], v[68:69], 0, v[0:1]
	v_or_b32_e32 v0, s53, v38
	s_waitcnt lgkmcnt(6)
	v_cvt_pk_bf16_f32 v48, v56, v54
	s_waitcnt lgkmcnt(4)
	v_cvt_pk_bf16_f32 v49, v58, v60
	s_waitcnt lgkmcnt(2)
	v_cvt_pk_bf16_f32 v50, v62, v64
	s_waitcnt lgkmcnt(0)
	v_cvt_pk_bf16_f32 v51, v66, v70
	v_lshlrev_b32_e32 v0, 11, v0
	global_store_dwordx4 v[52:53], v[48:51], off
	v_lshl_add_u64 v[52:53], v[68:69], 0, v[0:1]
	s_nop 0
	v_cvt_pk_bf16_f32 v48, v57, v55
	v_cvt_pk_bf16_f32 v49, v59, v61
	v_cvt_pk_bf16_f32 v50, v63, v65
	v_cvt_pk_bf16_f32 v51, v67, v71
	global_store_dwordx4 v[52:53], v[48:51], off
	s_waitcnt lgkmcnt(0)

.LBB0_42:
	s_andn2_b64 vcc, exec, s[2:3]
	s_cbranch_vccnz .LBB0_44
	s_add_i32 s0, s16, 0xffffea00
	s_and_b32 s2, s0, 0x1ffc0
	v_or_b32_e32 v0, s2, v34
	s_lshl_b32 s0, s53, 2
	v_lshl_add_u64 v[48:49], v[22:23], 0, s[0:1]
	v_lshlrev_b32_e32 v0, 12, v0
	v_lshl_add_u64 v[48:49], v[48:49], 0, v[0:1]
	v_add_co_u32_e32 v50, vcc, 0x2000, v48
	s_lshl_b32 s0, s2, 1
	s_nop 0
	v_addc_co_u32_e32 v51, vcc, 0, v49, vcc
	v_add_co_u32_e32 v52, vcc, 0x4000, v48
	s_nop 1
	v_addc_co_u32_e32 v53, vcc, 0, v49, vcc
	v_add_co_u32_e32 v54, vcc, 0x6000, v48
	s_nop 1
	v_addc_co_u32_e32 v55, vcc, 0, v49, vcc
	v_add_co_u32_e32 v56, vcc, 0x8000, v48
	s_nop 1
	v_addc_co_u32_e32 v57, vcc, 0, v49, vcc
	v_add_co_u32_e32 v58, vcc, 0xa000, v48
	s_nop 1
	v_addc_co_u32_e32 v59, vcc, 0, v49, vcc
	v_add_co_u32_e32 v60, vcc, 0xc000, v48
	s_nop 1
	v_addc_co_u32_e32 v61, vcc, 0, v49, vcc
	v_add_co_u32_e32 v62, vcc, 0xe000, v48
	s_nop 1
	v_addc_co_u32_e32 v63, vcc, 0, v49, vcc
	global_load_dword v0, v[48:49], off nt
	global_load_dword v66, v[50:51], off nt
	global_load_dword v67, v[52:53], off nt
	global_load_dword v68, v[54:55], off nt
	global_load_dword v69, v[56:57], off nt
	global_load_dword v70, v[58:59], off nt
	global_load_dword v71, v[60:61], off nt
	global_load_dword v72, v[62:63], off nt
	v_add_co_u32_e32 v50, vcc, 0x10000, v48
	s_nop 1
	v_addc_co_u32_e32 v51, vcc, 0, v49, vcc
	v_add_co_u32_e32 v52, vcc, 0x12000, v48
	s_nop 1
	v_addc_co_u32_e32 v53, vcc, 0, v49, vcc
	v_add_co_u32_e32 v54, vcc, 0x14000, v48
	s_nop 1
	v_addc_co_u32_e32 v55, vcc, 0, v49, vcc
	v_add_co_u32_e32 v56, vcc, 0x16000, v48
	s_nop 1
	v_addc_co_u32_e32 v57, vcc, 0, v49, vcc
	v_add_co_u32_e32 v58, vcc, 0x18000, v48
	s_nop 1
	v_addc_co_u32_e32 v59, vcc, 0, v49, vcc
	v_add_co_u32_e32 v60, vcc, 0x1a000, v48
	s_nop 1
	v_addc_co_u32_e32 v61, vcc, 0, v49, vcc
	v_add_co_u32_e32 v62, vcc, 0x1c000, v48
	s_nop 1
	v_addc_co_u32_e32 v63, vcc, 0, v49, vcc
	v_add_co_u32_e32 v64, vcc, 0x1e000, v48
	s_nop 1
	v_addc_co_u32_e32 v65, vcc, 0, v49, vcc
	global_load_dword v73, v[50:51], off nt
	global_load_dword v74, v[52:53], off nt
	global_load_dword v75, v[54:55], off nt
	global_load_dword v76, v[56:57], off nt
	global_load_dword v77, v[58:59], off nt
	global_load_dword v78, v[60:61], off nt
	global_load_dword v79, v[62:63], off nt
	global_load_dword v80, v[64:65], off nt
	v_add_co_u32_e32 v50, vcc, 0x20000, v48
	s_nop 1
	v_addc_co_u32_e32 v51, vcc, 0, v49, vcc
	v_add_co_u32_e32 v52, vcc, 0x22000, v48
	s_nop 1
	v_addc_co_u32_e32 v53, vcc, 0, v49, vcc
	v_add_co_u32_e32 v54, vcc, 0x24000, v48
	s_nop 1
	v_addc_co_u32_e32 v55, vcc, 0, v49, vcc
	v_add_co_u32_e32 v56, vcc, 0x26000, v48
	s_nop 1
	v_addc_co_u32_e32 v57, vcc, 0, v49, vcc
	v_add_co_u32_e32 v58, vcc, 0x28000, v48
	s_nop 1
	v_addc_co_u32_e32 v59, vcc, 0, v49, vcc
	v_add_co_u32_e32 v60, vcc, 0x2a000, v48
	s_nop 1
	v_addc_co_u32_e32 v61, vcc, 0, v49, vcc
	v_add_co_u32_e32 v62, vcc, 0x2c000, v48
	s_nop 1
	v_addc_co_u32_e32 v63, vcc, 0, v49, vcc
	v_add_co_u32_e32 v64, vcc, 0x2e000, v48
	s_nop 1
	v_addc_co_u32_e32 v65, vcc, 0, v49, vcc
	global_load_dword v81, v[50:51], off nt
	global_load_dword v82, v[52:53], off nt
	global_load_dword v83, v[54:55], off nt
	global_load_dword v84, v[56:57], off nt
	global_load_dword v85, v[58:59], off nt
	global_load_dword v86, v[60:61], off nt
	global_load_dword v87, v[62:63], off nt
	s_nop 0
	global_load_dword v64, v[64:65], off nt
	v_add_co_u32_e32 v50, vcc, 0x30000, v48
	s_nop 1
	v_addc_co_u32_e32 v51, vcc, 0, v49, vcc
	v_add_co_u32_e32 v52, vcc, 0x32000, v48
	s_nop 1
	v_addc_co_u32_e32 v53, vcc, 0, v49, vcc
	v_add_co_u32_e32 v54, vcc, 0x34000, v48
	s_nop 1
	v_addc_co_u32_e32 v55, vcc, 0, v49, vcc
	v_add_co_u32_e32 v56, vcc, 0x36000, v48
	s_nop 1
	v_addc_co_u32_e32 v57, vcc, 0, v49, vcc
	v_add_co_u32_e32 v58, vcc, 0x38000, v48
	s_nop 1
	v_addc_co_u32_e32 v59, vcc, 0, v49, vcc
	v_add_co_u32_e32 v60, vcc, 0x3a000, v48
	s_nop 1
	v_addc_co_u32_e32 v61, vcc, 0, v49, vcc
	v_add_co_u32_e32 v62, vcc, 0x3c000, v48
	s_nop 1
	v_addc_co_u32_e32 v63, vcc, 0, v49, vcc
	v_add_co_u32_e32 v48, vcc, 0x3e000, v48
	s_nop 1
	v_addc_co_u32_e32 v49, vcc, 0, v49, vcc
	global_load_dword v50, v[50:51], off nt
	s_nop 0
	global_load_dword v51, v[52:53], off nt
	s_nop 0
	global_load_dword v52, v[54:55], off nt
	global_load_dword v53, v[56:57], off nt
	s_nop 0
	global_load_dword v54, v[58:59], off nt
	global_load_dword v55, v[60:61], off nt
	global_load_dword v56, v[62:63], off nt
	s_nop 0
	global_load_dword v48, v[48:49], off nt
	s_waitcnt vmcnt(30)
	ds_write2_b32 v39, v0, v66 offset1:66
	s_waitcnt vmcnt(28)
	ds_write2_b32 v39, v67, v68 offset0:132 offset1:198
	s_waitcnt vmcnt(26)
	ds_write2_b32 v40, v69, v70 offset0:8 offset1:74
	s_waitcnt vmcnt(24)
	ds_write2_b32 v40, v71, v72 offset0:140 offset1:206
	s_waitcnt vmcnt(22)
	ds_write2_b32 v41, v73, v74 offset0:16 offset1:82
	s_waitcnt vmcnt(20)
	ds_write2_b32 v41, v75, v76 offset0:148 offset1:214
	s_waitcnt vmcnt(18)
	ds_write2_b32 v42, v77, v78 offset0:24 offset1:90
	s_waitcnt vmcnt(16)
	ds_write2_b32 v42, v79, v80 offset0:156 offset1:222
	s_waitcnt vmcnt(14)
	ds_write2_b32 v43, v81, v82 offset0:32 offset1:98
	s_waitcnt vmcnt(12)
	ds_write2_b32 v43, v83, v84 offset0:164 offset1:230
	s_waitcnt vmcnt(10)
	ds_write2_b32 v44, v85, v86 offset0:40 offset1:106
	s_waitcnt vmcnt(8)
	ds_write2_b32 v44, v87, v64 offset0:172 offset1:238
	s_waitcnt vmcnt(6)
	ds_write2_b32 v45, v50, v51 offset0:48 offset1:114
	s_waitcnt vmcnt(4)
	ds_write2_b32 v45, v52, v53 offset0:180 offset1:246
	s_waitcnt vmcnt(2)
	ds_write2_b32 v46, v54, v55 offset0:56 offset1:122
	s_waitcnt vmcnt(0)
	ds_write2_b32 v46, v56, v48 offset0:188 offset1:254
	s_waitcnt lgkmcnt(0)
	ds_read2_b32 v[52:53], v47 offset0:33 offset1:41
	ds_read2_b32 v[54:55], v47 offset1:8
	ds_read2_b32 v[56:57], v47 offset0:66 offset1:74
	ds_read2_b32 v[58:59], v47 offset0:99 offset1:107
	ds_read2_b32 v[60:61], v47 offset0:132 offset1:140
	ds_read2_b32 v[62:63], v47 offset0:165 offset1:173
	ds_read2_b32 v[64:65], v47 offset0:198 offset1:206
	ds_read2_b32 v[66:67], v47 offset0:231 offset1:239
	v_or_b32_e32 v0, s53, v35
	v_lshl_add_u64 v[68:69], v[6:7], 0, s[0:1]
	v_lshlrev_b32_e32 v0, 11, v0
	s_waitcnt lgkmcnt(6)
	v_cvt_pk_bf16_f32 v48, v54, v52
	s_waitcnt lgkmcnt(4)
	v_cvt_pk_bf16_f32 v49, v56, v58
	s_waitcnt lgkmcnt(2)
	v_cvt_pk_bf16_f32 v50, v60, v62
	s_waitcnt lgkmcnt(0)
	v_cvt_pk_bf16_f32 v51, v64, v66
	v_lshl_add_u64 v[70:71], v[68:69], 0, v[0:1]
	global_store_dwordx4 v[70:71], v[48:51], off
	v_or_b32_e32 v0, s53, v36
	v_lshlrev_b32_e32 v0, 11, v0
	v_cvt_pk_bf16_f32 v48, v55, v53
	v_cvt_pk_bf16_f32 v49, v57, v59
	v_cvt_pk_bf16_f32 v50, v61, v63
	v_cvt_pk_bf16_f32 v51, v65, v67
	ds_read2_b32 v[54:55], v47 offset0:49 offset1:57
	ds_read2_b32 v[56:57], v47 offset0:16 offset1:24
	ds_read2_b32 v[58:59], v47 offset0:82 offset1:90
	ds_read2_b32 v[60:61], v47 offset0:115 offset1:123
	ds_read2_b32 v[62:63], v47 offset0:148 offset1:156
	ds_read2_b32 v[64:65], v47 offset0:181 offset1:189
	ds_read2_b32 v[66:67], v47 offset0:214 offset1:222
	ds_read2_b32 v[70:71], v47 offset0:247 offset1:255
	v_lshl_add_u64 v[52:53], v[68:69], 0, v[0:1]
	v_or_b32_e32 v0, s53, v37
	v_lshlrev_b32_e32 v0, 11, v0
	global_store_dwordx4 v[52:53], v[48:51], off
	v_lshl_add_u64 v[52:53], v[68:69], 0, v[0:1]
	v_or_b32_e32 v0, s53, v38
	s_waitcnt lgkmcnt(6)
	v_cvt_pk_bf16_f32 v48, v56, v54
	s_waitcnt lgkmcnt(4)
	v_cvt_pk_bf16_f32 v49, v58, v60
	s_waitcnt lgkmcnt(2)
	v_cvt_pk_bf16_f32 v50, v62, v64
	s_waitcnt lgkmcnt(0)
	v_cvt_pk_bf16_f32 v51, v66, v70
	v_lshlrev_b32_e32 v0, 11, v0
	global_store_dwordx4 v[52:53], v[48:51], off
	v_lshl_add_u64 v[52:53], v[68:69], 0, v[0:1]
	s_nop 0
	v_cvt_pk_bf16_f32 v48, v57, v55
	v_cvt_pk_bf16_f32 v49, v59, v61
	v_cvt_pk_bf16_f32 v50, v63, v65
	v_cvt_pk_bf16_f32 v51, v67, v71
	global_store_dwordx4 v[52:53], v[48:51], off
	s_waitcnt lgkmcnt(0)

.LBB0_45:
	s_andn2_b64 vcc, exec, s[2:3]
	s_cbranch_vccnz .LBB0_47
	s_add_i32 s0, s16, 0xfffff500
	s_and_b32 s2, s0, 0x1ffc0
	v_or_b32_e32 v0, s2, v34
	s_lshl_b32 s0, s53, 2
	v_lshl_add_u64 v[48:49], v[24:25], 0, s[0:1]
	v_lshlrev_b32_e32 v0, 12, v0
	v_lshl_add_u64 v[48:49], v[48:49], 0, v[0:1]
	v_add_co_u32_e32 v50, vcc, 0x2000, v48
	s_lshl_b32 s0, s2, 1
	s_nop 0
	v_addc_co_u32_e32 v51, vcc, 0, v49, vcc
	v_add_co_u32_e32 v52, vcc, 0x4000, v48
	s_nop 1
	v_addc_co_u32_e32 v53, vcc, 0, v49, vcc
	v_add_co_u32_e32 v54, vcc, 0x6000, v48
	s_nop 1
	v_addc_co_u32_e32 v55, vcc, 0, v49, vcc
	v_add_co_u32_e32 v56, vcc, 0x8000, v48
	s_nop 1
	v_addc_co_u32_e32 v57, vcc, 0, v49, vcc
	v_add_co_u32_e32 v58, vcc, 0xa000, v48
	s_nop 1
	v_addc_co_u32_e32 v59, vcc, 0, v49, vcc
	v_add_co_u32_e32 v60, vcc, 0xc000, v48
	s_nop 1
	v_addc_co_u32_e32 v61, vcc, 0, v49, vcc
	v_add_co_u32_e32 v62, vcc, 0xe000, v48
	s_nop 1
	v_addc_co_u32_e32 v63, vcc, 0, v49, vcc
	global_load_dword v0, v[48:49], off nt
	global_load_dword v66, v[50:51], off nt
	global_load_dword v67, v[52:53], off nt
	global_load_dword v68, v[54:55], off nt
	global_load_dword v69, v[56:57], off nt
	global_load_dword v70, v[58:59], off nt
	global_load_dword v71, v[60:61], off nt
	global_load_dword v72, v[62:63], off nt
	v_add_co_u32_e32 v50, vcc, 0x10000, v48
	s_nop 1
	v_addc_co_u32_e32 v51, vcc, 0, v49, vcc
	v_add_co_u32_e32 v52, vcc, 0x12000, v48
	s_nop 1
	v_addc_co_u32_e32 v53, vcc, 0, v49, vcc
	v_add_co_u32_e32 v54, vcc, 0x14000, v48
	s_nop 1
	v_addc_co_u32_e32 v55, vcc, 0, v49, vcc
	v_add_co_u32_e32 v56, vcc, 0x16000, v48
	s_nop 1
	v_addc_co_u32_e32 v57, vcc, 0, v49, vcc
	v_add_co_u32_e32 v58, vcc, 0x18000, v48
	s_nop 1
	v_addc_co_u32_e32 v59, vcc, 0, v49, vcc
	v_add_co_u32_e32 v60, vcc, 0x1a000, v48
	s_nop 1
	v_addc_co_u32_e32 v61, vcc, 0, v49, vcc
	v_add_co_u32_e32 v62, vcc, 0x1c000, v48
	s_nop 1
	v_addc_co_u32_e32 v63, vcc, 0, v49, vcc
	v_add_co_u32_e32 v64, vcc, 0x1e000, v48
	s_nop 1
	v_addc_co_u32_e32 v65, vcc, 0, v49, vcc
	global_load_dword v73, v[50:51], off nt
	global_load_dword v74, v[52:53], off nt
	global_load_dword v75, v[54:55], off nt
	global_load_dword v76, v[56:57], off nt
	global_load_dword v77, v[58:59], off nt
	global_load_dword v78, v[60:61], off nt
	global_load_dword v79, v[62:63], off nt
	global_load_dword v80, v[64:65], off nt
	v_add_co_u32_e32 v50, vcc, 0x20000, v48
	s_nop 1
	v_addc_co_u32_e32 v51, vcc, 0, v49, vcc
	v_add_co_u32_e32 v52, vcc, 0x22000, v48
	s_nop 1
	v_addc_co_u32_e32 v53, vcc, 0, v49, vcc
	v_add_co_u32_e32 v54, vcc, 0x24000, v48
	s_nop 1
	v_addc_co_u32_e32 v55, vcc, 0, v49, vcc
	v_add_co_u32_e32 v56, vcc, 0x26000, v48
	s_nop 1
	v_addc_co_u32_e32 v57, vcc, 0, v49, vcc
	v_add_co_u32_e32 v58, vcc, 0x28000, v48
	s_nop 1
	v_addc_co_u32_e32 v59, vcc, 0, v49, vcc
	v_add_co_u32_e32 v60, vcc, 0x2a000, v48
	s_nop 1
	v_addc_co_u32_e32 v61, vcc, 0, v49, vcc
	v_add_co_u32_e32 v62, vcc, 0x2c000, v48
	s_nop 1
	v_addc_co_u32_e32 v63, vcc, 0, v49, vcc
	v_add_co_u32_e32 v64, vcc, 0x2e000, v48
	s_nop 1
	v_addc_co_u32_e32 v65, vcc, 0, v49, vcc
	global_load_dword v81, v[50:51], off nt
	global_load_dword v82, v[52:53], off nt
	global_load_dword v83, v[54:55], off nt
	global_load_dword v84, v[56:57], off nt
	global_load_dword v85, v[58:59], off nt
	global_load_dword v86, v[60:61], off nt
	global_load_dword v87, v[62:63], off nt
	s_nop 0
	global_load_dword v64, v[64:65], off nt
	v_add_co_u32_e32 v50, vcc, 0x30000, v48
	s_nop 1
	v_addc_co_u32_e32 v51, vcc, 0, v49, vcc
	v_add_co_u32_e32 v52, vcc, 0x32000, v48
	s_nop 1
	v_addc_co_u32_e32 v53, vcc, 0, v49, vcc
	v_add_co_u32_e32 v54, vcc, 0x34000, v48
	s_nop 1
	v_addc_co_u32_e32 v55, vcc, 0, v49, vcc
	v_add_co_u32_e32 v56, vcc, 0x36000, v48
	s_nop 1
	v_addc_co_u32_e32 v57, vcc, 0, v49, vcc
	v_add_co_u32_e32 v58, vcc, 0x38000, v48
	s_nop 1
	v_addc_co_u32_e32 v59, vcc, 0, v49, vcc
	v_add_co_u32_e32 v60, vcc, 0x3a000, v48
	s_nop 1
	v_addc_co_u32_e32 v61, vcc, 0, v49, vcc
	v_add_co_u32_e32 v62, vcc, 0x3c000, v48
	s_nop 1
	v_addc_co_u32_e32 v63, vcc, 0, v49, vcc
	v_add_co_u32_e32 v48, vcc, 0x3e000, v48
	s_nop 1
	v_addc_co_u32_e32 v49, vcc, 0, v49, vcc
	global_load_dword v50, v[50:51], off nt
	s_nop 0
	global_load_dword v51, v[52:53], off nt
	s_nop 0
	global_load_dword v52, v[54:55], off nt
	global_load_dword v53, v[56:57], off nt
	s_nop 0
	global_load_dword v54, v[58:59], off nt
	global_load_dword v55, v[60:61], off nt
	global_load_dword v56, v[62:63], off nt
	s_nop 0
	global_load_dword v48, v[48:49], off nt
	s_waitcnt vmcnt(30)
	ds_write2_b32 v39, v0, v66 offset1:66
	s_waitcnt vmcnt(28)
	ds_write2_b32 v39, v67, v68 offset0:132 offset1:198
	s_waitcnt vmcnt(26)
	ds_write2_b32 v40, v69, v70 offset0:8 offset1:74
	s_waitcnt vmcnt(24)
	ds_write2_b32 v40, v71, v72 offset0:140 offset1:206
	s_waitcnt vmcnt(22)
	ds_write2_b32 v41, v73, v74 offset0:16 offset1:82
	s_waitcnt vmcnt(20)
	ds_write2_b32 v41, v75, v76 offset0:148 offset1:214
	s_waitcnt vmcnt(18)
	ds_write2_b32 v42, v77, v78 offset0:24 offset1:90
	s_waitcnt vmcnt(16)
	ds_write2_b32 v42, v79, v80 offset0:156 offset1:222
	s_waitcnt vmcnt(14)
	ds_write2_b32 v43, v81, v82 offset0:32 offset1:98
	s_waitcnt vmcnt(12)
	ds_write2_b32 v43, v83, v84 offset0:164 offset1:230
	s_waitcnt vmcnt(10)
	ds_write2_b32 v44, v85, v86 offset0:40 offset1:106
	s_waitcnt vmcnt(8)
	ds_write2_b32 v44, v87, v64 offset0:172 offset1:238
	s_waitcnt vmcnt(6)
	ds_write2_b32 v45, v50, v51 offset0:48 offset1:114
	s_waitcnt vmcnt(4)
	ds_write2_b32 v45, v52, v53 offset0:180 offset1:246
	s_waitcnt vmcnt(2)
	ds_write2_b32 v46, v54, v55 offset0:56 offset1:122
	s_waitcnt vmcnt(0)
	ds_write2_b32 v46, v56, v48 offset0:188 offset1:254
	s_waitcnt lgkmcnt(0)
	ds_read2_b32 v[52:53], v47 offset0:33 offset1:41
	ds_read2_b32 v[54:55], v47 offset1:8
	ds_read2_b32 v[56:57], v47 offset0:66 offset1:74
	ds_read2_b32 v[58:59], v47 offset0:99 offset1:107
	ds_read2_b32 v[60:61], v47 offset0:132 offset1:140
	ds_read2_b32 v[62:63], v47 offset0:165 offset1:173
	ds_read2_b32 v[64:65], v47 offset0:198 offset1:206
	ds_read2_b32 v[66:67], v47 offset0:231 offset1:239
	v_or_b32_e32 v0, s53, v35
	v_lshl_add_u64 v[68:69], v[8:9], 0, s[0:1]
	v_mul_u32_u24_e32 v0, 0x1600, v0
	s_waitcnt lgkmcnt(6)
	v_cvt_pk_bf16_f32 v48, v54, v52
	s_waitcnt lgkmcnt(4)
	v_cvt_pk_bf16_f32 v49, v56, v58
	s_waitcnt lgkmcnt(2)
	v_cvt_pk_bf16_f32 v50, v60, v62
	s_waitcnt lgkmcnt(0)
	v_cvt_pk_bf16_f32 v51, v64, v66
	v_lshl_add_u64 v[70:71], v[68:69], 0, v[0:1]
	global_store_dwordx4 v[70:71], v[48:51], off
	v_or_b32_e32 v0, s53, v36
	v_mul_u32_u24_e32 v0, 0x1600, v0
	v_cvt_pk_bf16_f32 v48, v55, v53
	v_cvt_pk_bf16_f32 v49, v57, v59
	v_cvt_pk_bf16_f32 v50, v61, v63
	v_cvt_pk_bf16_f32 v51, v65, v67
	ds_read2_b32 v[54:55], v47 offset0:16 offset1:24
	ds_read2_b32 v[56:57], v47 offset0:49 offset1:57
	ds_read2_b32 v[58:59], v47 offset0:82 offset1:90
	ds_read2_b32 v[60:61], v47 offset0:115 offset1:123
	ds_read2_b32 v[62:63], v47 offset0:148 offset1:156
	ds_read2_b32 v[64:65], v47 offset0:181 offset1:189
	ds_read2_b32 v[66:67], v47 offset0:214 offset1:222
	ds_read2_b32 v[70:71], v47 offset0:247 offset1:255
	v_lshl_add_u64 v[52:53], v[68:69], 0, v[0:1]
	v_or_b32_e32 v0, s53, v37
	v_mul_u32_u24_e32 v0, 0x1600, v0
	global_store_dwordx4 v[52:53], v[48:51], off
	v_lshl_add_u64 v[52:53], v[68:69], 0, v[0:1]
	v_or_b32_e32 v0, s53, v38
	s_waitcnt lgkmcnt(6)
	v_cvt_pk_bf16_f32 v48, v54, v56
	s_waitcnt lgkmcnt(4)
	v_cvt_pk_bf16_f32 v49, v58, v60
	s_waitcnt lgkmcnt(2)
	v_cvt_pk_bf16_f32 v50, v62, v64
	s_waitcnt lgkmcnt(0)
	v_cvt_pk_bf16_f32 v51, v66, v70
	v_mul_u32_u24_e32 v0, 0x1600, v0
	global_store_dwordx4 v[52:53], v[48:51], off
	v_lshl_add_u64 v[52:53], v[68:69], 0, v[0:1]
	s_nop 0
	v_cvt_pk_bf16_f32 v48, v55, v57
	v_cvt_pk_bf16_f32 v49, v59, v61
	v_cvt_pk_bf16_f32 v50, v63, v65
	v_cvt_pk_bf16_f32 v51, v67, v71
	global_store_dwordx4 v[52:53], v[48:51], off
	s_waitcnt lgkmcnt(0)

.LBB0_48:
	s_andn2_b64 vcc, exec, s[2:3]
	s_cbranch_vccnz .LBB0_50
	s_and_b32 s2, s16, 0x1ffc0
	v_or_b32_e32 v0, s2, v34
	s_lshl_b32 s0, s53, 2
	v_lshl_add_u64 v[48:49], v[26:27], 0, s[0:1]
	v_lshlrev_b32_e32 v0, 12, v0
	v_lshl_add_u64 v[48:49], v[48:49], 0, v[0:1]
	v_add_co_u32_e32 v50, vcc, 0x2000, v48
	s_lshl_b32 s0, s2, 1
	s_nop 0
	v_addc_co_u32_e32 v51, vcc, 0, v49, vcc
	v_add_co_u32_e32 v52, vcc, 0x4000, v48
	s_nop 1
	v_addc_co_u32_e32 v53, vcc, 0, v49, vcc
	v_add_co_u32_e32 v54, vcc, 0x6000, v48
	s_nop 1
	v_addc_co_u32_e32 v55, vcc, 0, v49, vcc
	v_add_co_u32_e32 v56, vcc, 0x8000, v48
	s_nop 1
	v_addc_co_u32_e32 v57, vcc, 0, v49, vcc
	v_add_co_u32_e32 v58, vcc, 0xa000, v48
	s_nop 1
	v_addc_co_u32_e32 v59, vcc, 0, v49, vcc
	v_add_co_u32_e32 v60, vcc, 0xc000, v48
	s_nop 1
	v_addc_co_u32_e32 v61, vcc, 0, v49, vcc
	v_add_co_u32_e32 v62, vcc, 0xe000, v48
	s_nop 1
	v_addc_co_u32_e32 v63, vcc, 0, v49, vcc
	global_load_dword v0, v[48:49], off nt
	global_load_dword v66, v[50:51], off nt
	global_load_dword v67, v[52:53], off nt
	global_load_dword v68, v[54:55], off nt
	global_load_dword v69, v[56:57], off nt
	global_load_dword v70, v[58:59], off nt
	global_load_dword v71, v[60:61], off nt
	global_load_dword v72, v[62:63], off nt
	v_add_co_u32_e32 v50, vcc, 0x10000, v48
	s_nop 1
	v_addc_co_u32_e32 v51, vcc, 0, v49, vcc
	v_add_co_u32_e32 v52, vcc, 0x12000, v48
	s_nop 1
	v_addc_co_u32_e32 v53, vcc, 0, v49, vcc
	v_add_co_u32_e32 v54, vcc, 0x14000, v48
	s_nop 1
	v_addc_co_u32_e32 v55, vcc, 0, v49, vcc
	v_add_co_u32_e32 v56, vcc, 0x16000, v48
	s_nop 1
	v_addc_co_u32_e32 v57, vcc, 0, v49, vcc
	v_add_co_u32_e32 v58, vcc, 0x18000, v48
	s_nop 1
	v_addc_co_u32_e32 v59, vcc, 0, v49, vcc
	v_add_co_u32_e32 v60, vcc, 0x1a000, v48
	s_nop 1
	v_addc_co_u32_e32 v61, vcc, 0, v49, vcc
	v_add_co_u32_e32 v62, vcc, 0x1c000, v48
	s_nop 1
	v_addc_co_u32_e32 v63, vcc, 0, v49, vcc
	v_add_co_u32_e32 v64, vcc, 0x1e000, v48
	s_nop 1
	v_addc_co_u32_e32 v65, vcc, 0, v49, vcc
	global_load_dword v73, v[50:51], off nt
	global_load_dword v74, v[52:53], off nt
	global_load_dword v75, v[54:55], off nt
	global_load_dword v76, v[56:57], off nt
	global_load_dword v77, v[58:59], off nt
	global_load_dword v78, v[60:61], off nt
	global_load_dword v79, v[62:63], off nt
	global_load_dword v80, v[64:65], off nt
	v_add_co_u32_e32 v50, vcc, 0x20000, v48
	s_nop 1
	v_addc_co_u32_e32 v51, vcc, 0, v49, vcc
	v_add_co_u32_e32 v52, vcc, 0x22000, v48
	s_nop 1
	v_addc_co_u32_e32 v53, vcc, 0, v49, vcc
	v_add_co_u32_e32 v54, vcc, 0x24000, v48
	s_nop 1
	v_addc_co_u32_e32 v55, vcc, 0, v49, vcc
	v_add_co_u32_e32 v56, vcc, 0x26000, v48
	s_nop 1
	v_addc_co_u32_e32 v57, vcc, 0, v49, vcc
	v_add_co_u32_e32 v58, vcc, 0x28000, v48
	s_nop 1
	v_addc_co_u32_e32 v59, vcc, 0, v49, vcc
	v_add_co_u32_e32 v60, vcc, 0x2a000, v48
	s_nop 1
	v_addc_co_u32_e32 v61, vcc, 0, v49, vcc
	v_add_co_u32_e32 v62, vcc, 0x2c000, v48
	s_nop 1
	v_addc_co_u32_e32 v63, vcc, 0, v49, vcc
	v_add_co_u32_e32 v64, vcc, 0x2e000, v48
	s_nop 1
	v_addc_co_u32_e32 v65, vcc, 0, v49, vcc
	global_load_dword v81, v[50:51], off nt
	global_load_dword v82, v[52:53], off nt
	global_load_dword v83, v[54:55], off nt
	global_load_dword v84, v[56:57], off nt
	global_load_dword v85, v[58:59], off nt
	global_load_dword v86, v[60:61], off nt
	global_load_dword v87, v[62:63], off nt
	s_nop 0
	global_load_dword v64, v[64:65], off nt
	v_add_co_u32_e32 v50, vcc, 0x30000, v48
	s_nop 1
	v_addc_co_u32_e32 v51, vcc, 0, v49, vcc
	v_add_co_u32_e32 v52, vcc, 0x32000, v48
	s_nop 1
	v_addc_co_u32_e32 v53, vcc, 0, v49, vcc
	v_add_co_u32_e32 v54, vcc, 0x34000, v48
	s_nop 1
	v_addc_co_u32_e32 v55, vcc, 0, v49, vcc
	v_add_co_u32_e32 v56, vcc, 0x36000, v48
	s_nop 1
	v_addc_co_u32_e32 v57, vcc, 0, v49, vcc
	v_add_co_u32_e32 v58, vcc, 0x38000, v48
	s_nop 1
	v_addc_co_u32_e32 v59, vcc, 0, v49, vcc
	v_add_co_u32_e32 v60, vcc, 0x3a000, v48
	s_nop 1
	v_addc_co_u32_e32 v61, vcc, 0, v49, vcc
	v_add_co_u32_e32 v62, vcc, 0x3c000, v48
	s_nop 1
	v_addc_co_u32_e32 v63, vcc, 0, v49, vcc
	v_add_co_u32_e32 v48, vcc, 0x3e000, v48
	s_nop 1
	v_addc_co_u32_e32 v49, vcc, 0, v49, vcc
	global_load_dword v50, v[50:51], off nt
	s_nop 0
	global_load_dword v51, v[52:53], off nt
	s_nop 0
	global_load_dword v52, v[54:55], off nt
	global_load_dword v53, v[56:57], off nt
	s_nop 0
	global_load_dword v54, v[58:59], off nt
	global_load_dword v55, v[60:61], off nt
	global_load_dword v56, v[62:63], off nt
	s_nop 0
	global_load_dword v48, v[48:49], off nt
	s_waitcnt vmcnt(30)
	ds_write2_b32 v39, v0, v66 offset1:66
	s_waitcnt vmcnt(28)
	ds_write2_b32 v39, v67, v68 offset0:132 offset1:198
	s_waitcnt vmcnt(26)
	ds_write2_b32 v40, v69, v70 offset0:8 offset1:74
	s_waitcnt vmcnt(24)
	ds_write2_b32 v40, v71, v72 offset0:140 offset1:206
	s_waitcnt vmcnt(22)
	ds_write2_b32 v41, v73, v74 offset0:16 offset1:82
	s_waitcnt vmcnt(20)
	ds_write2_b32 v41, v75, v76 offset0:148 offset1:214
	s_waitcnt vmcnt(18)
	ds_write2_b32 v42, v77, v78 offset0:24 offset1:90
	s_waitcnt vmcnt(16)
	ds_write2_b32 v42, v79, v80 offset0:156 offset1:222
	s_waitcnt vmcnt(14)
	ds_write2_b32 v43, v81, v82 offset0:32 offset1:98
	s_waitcnt vmcnt(12)
	ds_write2_b32 v43, v83, v84 offset0:164 offset1:230
	s_waitcnt vmcnt(10)
	ds_write2_b32 v44, v85, v86 offset0:40 offset1:106
	s_waitcnt vmcnt(8)
	ds_write2_b32 v44, v87, v64 offset0:172 offset1:238
	s_waitcnt vmcnt(6)
	ds_write2_b32 v45, v50, v51 offset0:48 offset1:114
	s_waitcnt vmcnt(4)
	ds_write2_b32 v45, v52, v53 offset0:180 offset1:246
	s_waitcnt vmcnt(2)
	ds_write2_b32 v46, v54, v55 offset0:56 offset1:122
	s_waitcnt vmcnt(0)
	ds_write2_b32 v46, v56, v48 offset0:188 offset1:254
	s_waitcnt lgkmcnt(0)
	ds_read2_b32 v[52:53], v47 offset0:33 offset1:41
	ds_read2_b32 v[54:55], v47 offset1:8
	ds_read2_b32 v[56:57], v47 offset0:66 offset1:74
	ds_read2_b32 v[58:59], v47 offset0:99 offset1:107
	ds_read2_b32 v[60:61], v47 offset0:132 offset1:140
	ds_read2_b32 v[62:63], v47 offset0:165 offset1:173
	ds_read2_b32 v[64:65], v47 offset0:198 offset1:206
	ds_read2_b32 v[66:67], v47 offset0:231 offset1:239
	v_or_b32_e32 v0, s53, v35
	v_lshl_add_u64 v[68:69], v[10:11], 0, s[0:1]
	v_mul_u32_u24_e32 v0, 0x1600, v0
	s_waitcnt lgkmcnt(6)
	v_cvt_pk_bf16_f32 v48, v54, v52
	s_waitcnt lgkmcnt(4)
	v_cvt_pk_bf16_f32 v49, v56, v58
	s_waitcnt lgkmcnt(2)
	v_cvt_pk_bf16_f32 v50, v60, v62
	s_waitcnt lgkmcnt(0)
	v_cvt_pk_bf16_f32 v51, v64, v66
	v_lshl_add_u64 v[70:71], v[68:69], 0, v[0:1]
	global_store_dwordx4 v[70:71], v[48:51], off
	v_or_b32_e32 v0, s53, v36
	v_mul_u32_u24_e32 v0, 0x1600, v0
	v_cvt_pk_bf16_f32 v48, v55, v53
	v_cvt_pk_bf16_f32 v49, v57, v59
	v_cvt_pk_bf16_f32 v50, v61, v63
	v_cvt_pk_bf16_f32 v51, v65, v67
	ds_read2_b32 v[54:55], v47 offset0:16 offset1:24
	ds_read2_b32 v[56:57], v47 offset0:49 offset1:57
	ds_read2_b32 v[58:59], v47 offset0:82 offset1:90
	ds_read2_b32 v[60:61], v47 offset0:115 offset1:123
	ds_read2_b32 v[62:63], v47 offset0:148 offset1:156
	ds_read2_b32 v[64:65], v47 offset0:181 offset1:189
	ds_read2_b32 v[66:67], v47 offset0:214 offset1:222
	ds_read2_b32 v[70:71], v47 offset0:247 offset1:255
	v_lshl_add_u64 v[52:53], v[68:69], 0, v[0:1]
	v_or_b32_e32 v0, s53, v37
	v_mul_u32_u24_e32 v0, 0x1600, v0
	global_store_dwordx4 v[52:53], v[48:51], off
	v_lshl_add_u64 v[52:53], v[68:69], 0, v[0:1]
	v_or_b32_e32 v0, s53, v38
	s_waitcnt lgkmcnt(6)
	v_cvt_pk_bf16_f32 v48, v54, v56
	s_waitcnt lgkmcnt(4)
	v_cvt_pk_bf16_f32 v49, v58, v60
	s_waitcnt lgkmcnt(2)
	v_cvt_pk_bf16_f32 v50, v62, v64
	s_waitcnt lgkmcnt(0)
	v_cvt_pk_bf16_f32 v51, v66, v70
	v_mul_u32_u24_e32 v0, 0x1600, v0
	global_store_dwordx4 v[52:53], v[48:51], off
	v_lshl_add_u64 v[52:53], v[68:69], 0, v[0:1]
	s_nop 0
	v_cvt_pk_bf16_f32 v48, v55, v57
	v_cvt_pk_bf16_f32 v49, v59, v61
	v_cvt_pk_bf16_f32 v50, v63, v65
	v_cvt_pk_bf16_f32 v51, v67, v71
	global_store_dwordx4 v[52:53], v[48:51], off
	s_waitcnt lgkmcnt(0)

.LBB0_51:
	s_andn2_b64 vcc, exec, s[2:3]
	s_cbranch_vccnz .LBB0_53
	s_add_i32 s0, s4, 0xe300
	s_and_b32 s2, s0, 0xffff
	s_mul_i32 s2, s2, 0xba2f
	s_lshr_b32 s2, s2, 23
	s_mul_i32 s3, s2, 0xb0
	s_sub_i32 s0, s0, s3
	s_lshl_b32 s3, s0, 5
	s_and_b32 s53, s3, 0xffe0
	s_and_b32 s0, s0, 0xffff
	s_cmpk_gt_u32 s0, 0x57
	s_cselect_b32 s55, 0xfffff500, 0
	s_cselect_b32 s54, 0x80, 0
	v_lshl_or_b32 v0, s2, 6, v34
	s_lshl_b32 s0, s53, 2
	v_lshl_add_u64 v[48:49], v[28:29], 0, s[0:1]
	v_mul_u32_u24_e32 v0, 0x5800, v0
	v_lshl_add_u64 v[48:49], v[48:49], 0, v[0:1]
	v_add_co_u32_e32 v50, vcc, s20, v48
	s_add_i32 s55, s55, s53
	s_nop 0
	v_addc_co_u32_e32 v51, vcc, 0, v49, vcc
	v_add_co_u32_e32 v52, vcc, s18, v48
	s_lshl_b32 s0, s55, 1
	s_nop 0
	v_addc_co_u32_e32 v53, vcc, 0, v49, vcc
	v_add_co_u32_e32 v54, vcc, s21, v48
	s_and_b32 s3, s3, 0x60
	s_nop 0
	v_addc_co_u32_e32 v55, vcc, 0, v49, vcc
	v_add_co_u32_e32 v56, vcc, s19, v48
	s_and_b32 s0, s0, 0xffffff00
	s_nop 0
	v_addc_co_u32_e32 v57, vcc, 0, v49, vcc
	v_add_co_u32_e32 v58, vcc, s22, v48
	s_or_b32 s3, s3, s54
	s_nop 0
	v_addc_co_u32_e32 v59, vcc, 0, v49, vcc
	v_add_co_u32_e32 v60, vcc, s23, v48
	s_or_b32 s3, s3, s0
	s_nop 0
	v_addc_co_u32_e32 v61, vcc, 0, v49, vcc
	v_add_co_u32_e32 v62, vcc, s24, v48
	s_lshl_b32 s0, s2, 7
	s_nop 0
	v_addc_co_u32_e32 v63, vcc, 0, v49, vcc
	global_load_dword v0, v[48:49], off nt
	global_load_dword v66, v[50:51], off nt
	global_load_dword v67, v[52:53], off nt
	global_load_dword v68, v[54:55], off nt
	global_load_dword v69, v[56:57], off nt
	global_load_dword v70, v[58:59], off nt
	global_load_dword v71, v[60:61], off nt
	global_load_dword v72, v[62:63], off nt
	v_add_co_u32_e32 v50, vcc, s25, v48
	s_nop 1
	v_addc_co_u32_e32 v51, vcc, 0, v49, vcc
	v_add_co_u32_e32 v52, vcc, s26, v48
	s_nop 1
	v_addc_co_u32_e32 v53, vcc, 0, v49, vcc
	v_add_co_u32_e32 v54, vcc, s27, v48
	s_nop 1
	v_addc_co_u32_e32 v55, vcc, 0, v49, vcc
	v_add_co_u32_e32 v56, vcc, s28, v48
	s_nop 1
	v_addc_co_u32_e32 v57, vcc, 0, v49, vcc
	v_add_co_u32_e32 v58, vcc, s29, v48
	s_nop 1
	v_addc_co_u32_e32 v59, vcc, 0, v49, vcc
	v_add_co_u32_e32 v60, vcc, s30, v48
	s_nop 1
	v_addc_co_u32_e32 v61, vcc, 0, v49, vcc
	v_add_co_u32_e32 v62, vcc, s31, v48
	s_nop 1
	v_addc_co_u32_e32 v63, vcc, 0, v49, vcc
	v_add_co_u32_e32 v64, vcc, s34, v48
	s_nop 1
	v_addc_co_u32_e32 v65, vcc, 0, v49, vcc
	global_load_dword v73, v[50:51], off nt
	global_load_dword v74, v[52:53], off nt
	global_load_dword v75, v[54:55], off nt
	global_load_dword v76, v[56:57], off nt
	global_load_dword v77, v[58:59], off nt
	global_load_dword v78, v[60:61], off nt
	global_load_dword v79, v[62:63], off nt
	global_load_dword v80, v[64:65], off nt
	v_add_co_u32_e32 v50, vcc, s35, v48
	s_nop 1
	v_addc_co_u32_e32 v51, vcc, 0, v49, vcc
	v_add_co_u32_e32 v52, vcc, s36, v48
	s_nop 1
	v_addc_co_u32_e32 v53, vcc, 0, v49, vcc
	v_add_co_u32_e32 v54, vcc, s37, v48
	s_nop 1
	v_addc_co_u32_e32 v55, vcc, 0, v49, vcc
	v_add_co_u32_e32 v56, vcc, s38, v48
	s_nop 1
	v_addc_co_u32_e32 v57, vcc, 0, v49, vcc
	v_add_co_u32_e32 v58, vcc, s39, v48
	s_nop 1
	v_addc_co_u32_e32 v59, vcc, 0, v49, vcc
	v_add_co_u32_e32 v60, vcc, s40, v48
	s_nop 1
	v_addc_co_u32_e32 v61, vcc, 0, v49, vcc
	v_add_co_u32_e32 v62, vcc, s41, v48
	s_nop 1
	v_addc_co_u32_e32 v63, vcc, 0, v49, vcc
	v_add_co_u32_e32 v64, vcc, s42, v48
	s_nop 1
	v_addc_co_u32_e32 v65, vcc, 0, v49, vcc
	global_load_dword v81, v[50:51], off nt
	global_load_dword v82, v[52:53], off nt
	global_load_dword v83, v[54:55], off nt
	global_load_dword v84, v[56:57], off nt
	global_load_dword v85, v[58:59], off nt
	global_load_dword v86, v[60:61], off nt
	global_load_dword v87, v[62:63], off nt
	s_nop 0
	global_load_dword v64, v[64:65], off nt
	v_add_co_u32_e32 v50, vcc, s43, v48
	s_nop 1
	v_addc_co_u32_e32 v51, vcc, 0, v49, vcc
	v_add_co_u32_e32 v52, vcc, s44, v48
	s_nop 1
	v_addc_co_u32_e32 v53, vcc, 0, v49, vcc
	v_add_co_u32_e32 v54, vcc, s45, v48
	s_nop 1
	v_addc_co_u32_e32 v55, vcc, 0, v49, vcc
	v_add_co_u32_e32 v56, vcc, s46, v48
	s_nop 1
	v_addc_co_u32_e32 v57, vcc, 0, v49, vcc
	v_add_co_u32_e32 v58, vcc, s47, v48
	s_nop 1
	v_addc_co_u32_e32 v59, vcc, 0, v49, vcc
	v_add_co_u32_e32 v60, vcc, s48, v48
	s_nop 1
	v_addc_co_u32_e32 v61, vcc, 0, v49, vcc
	v_add_co_u32_e32 v62, vcc, s49, v48
	s_nop 1
	v_addc_co_u32_e32 v63, vcc, 0, v49, vcc
	v_add_co_u32_e32 v48, vcc, s51, v48
	s_nop 1
	v_addc_co_u32_e32 v49, vcc, 0, v49, vcc
	global_load_dword v50, v[50:51], off nt
	s_nop 0
	global_load_dword v51, v[52:53], off nt
	s_nop 0
	global_load_dword v52, v[54:55], off nt
	global_load_dword v53, v[56:57], off nt
	s_nop 0
	global_load_dword v54, v[58:59], off nt
	global_load_dword v55, v[60:61], off nt
	global_load_dword v56, v[62:63], off nt
	s_nop 0
	global_load_dword v48, v[48:49], off nt
	s_waitcnt vmcnt(30)
	ds_write2_b32 v39, v0, v66 offset1:66
	s_waitcnt vmcnt(28)
	ds_write2_b32 v39, v67, v68 offset0:132 offset1:198
	s_waitcnt vmcnt(26)
	ds_write2_b32 v40, v69, v70 offset0:8 offset1:74
	s_waitcnt vmcnt(24)
	ds_write2_b32 v40, v71, v72 offset0:140 offset1:206
	s_waitcnt vmcnt(22)
	ds_write2_b32 v41, v73, v74 offset0:16 offset1:82
	s_waitcnt vmcnt(20)
	ds_write2_b32 v41, v75, v76 offset0:148 offset1:214
	s_waitcnt vmcnt(18)
	ds_write2_b32 v42, v77, v78 offset0:24 offset1:90
	s_waitcnt vmcnt(16)
	ds_write2_b32 v42, v79, v80 offset0:156 offset1:222
	s_waitcnt vmcnt(14)
	ds_write2_b32 v43, v81, v82 offset0:32 offset1:98
	s_waitcnt vmcnt(12)
	ds_write2_b32 v43, v83, v84 offset0:164 offset1:230
	s_waitcnt vmcnt(10)
	ds_write2_b32 v44, v85, v86 offset0:40 offset1:106
	s_waitcnt vmcnt(8)
	ds_write2_b32 v44, v87, v64 offset0:172 offset1:238
	s_waitcnt vmcnt(6)
	ds_write2_b32 v45, v50, v51 offset0:48 offset1:114
	s_waitcnt vmcnt(4)
	ds_write2_b32 v45, v52, v53 offset0:180 offset1:246
	s_waitcnt vmcnt(2)
	ds_write2_b32 v46, v54, v55 offset0:56 offset1:122
	s_waitcnt vmcnt(0)
	ds_write2_b32 v46, v56, v48 offset0:188 offset1:254
	s_waitcnt lgkmcnt(0)
	ds_read2_b32 v[52:53], v47 offset0:33 offset1:41
	ds_read2_b32 v[54:55], v47 offset1:8
	ds_read2_b32 v[56:57], v47 offset0:66 offset1:74
	ds_read2_b32 v[58:59], v47 offset0:99 offset1:107
	ds_read2_b32 v[60:61], v47 offset0:132 offset1:140
	ds_read2_b32 v[62:63], v47 offset0:165 offset1:173
	ds_read2_b32 v[64:65], v47 offset0:198 offset1:206
	ds_read2_b32 v[66:67], v47 offset0:231 offset1:239
	v_or_b32_e32 v70, s3, v35
	v_ashrrev_i32_e32 v71, 31, v70
	v_lshl_add_u64 v[68:69], v[12:13], 0, s[0:1]
	v_lshlrev_b64 v[70:71], 11, v[70:71]
	s_waitcnt lgkmcnt(6)
	v_cvt_pk_bf16_f32 v48, v54, v52
	s_waitcnt lgkmcnt(4)
	v_cvt_pk_bf16_f32 v49, v56, v58
	s_waitcnt lgkmcnt(2)
	v_cvt_pk_bf16_f32 v50, v60, v62
	s_waitcnt lgkmcnt(0)
	v_cvt_pk_bf16_f32 v51, v64, v66
	v_lshl_add_u64 v[70:71], v[68:69], 0, v[70:71]
	v_or_b32_e32 v52, s3, v36
	global_store_dwordx4 v[70:71], v[48:51], off
	s_nop 1
	v_cvt_pk_bf16_f32 v48, v55, v53
	v_ashrrev_i32_e32 v53, 31, v52
	v_cvt_pk_bf16_f32 v49, v57, v59
	v_cvt_pk_bf16_f32 v50, v61, v63
	v_cvt_pk_bf16_f32 v51, v65, v67
	v_lshlrev_b64 v[52:53], 11, v[52:53]
	ds_read2_b32 v[54:55], v47 offset0:49 offset1:57
	ds_read2_b32 v[56:57], v47 offset0:16 offset1:24
	ds_read2_b32 v[58:59], v47 offset0:82 offset1:90
	ds_read2_b32 v[60:61], v47 offset0:115 offset1:123
	ds_read2_b32 v[62:63], v47 offset0:148 offset1:156
	ds_read2_b32 v[64:65], v47 offset0:181 offset1:189
	ds_read2_b32 v[66:67], v47 offset0:214 offset1:222
	ds_read2_b32 v[70:71], v47 offset0:247 offset1:255
	v_lshl_add_u64 v[52:53], v[68:69], 0, v[52:53]
	global_store_dwordx4 v[52:53], v[48:51], off
	v_or_b32_e32 v52, s3, v37
	v_ashrrev_i32_e32 v53, 31, v52
	v_lshlrev_b64 v[52:53], 11, v[52:53]
	s_waitcnt lgkmcnt(6)
	v_cvt_pk_bf16_f32 v48, v56, v54
	s_waitcnt lgkmcnt(4)
	v_cvt_pk_bf16_f32 v49, v58, v60
	s_waitcnt lgkmcnt(2)
	v_cvt_pk_bf16_f32 v50, v62, v64
	s_waitcnt lgkmcnt(0)
	v_cvt_pk_bf16_f32 v51, v66, v70
	v_lshl_add_u64 v[52:53], v[68:69], 0, v[52:53]
	global_store_dwordx4 v[52:53], v[48:51], off
	v_or_b32_e32 v52, s3, v38
	v_ashrrev_i32_e32 v53, 31, v52
	v_lshlrev_b64 v[52:53], 11, v[52:53]
	v_cvt_pk_bf16_f32 v48, v57, v55
	v_cvt_pk_bf16_f32 v49, v59, v61
	v_cvt_pk_bf16_f32 v50, v63, v65
	v_cvt_pk_bf16_f32 v51, v67, v71
	v_lshl_add_u64 v[52:53], v[68:69], 0, v[52:53]
	global_store_dwordx4 v[52:53], v[48:51], off
	s_waitcnt lgkmcnt(0)

.LBB0_54:
	s_andn2_b64 vcc, exec, s[2:3]
	s_cbranch_vccnz .LBB0_56
	s_add_i32 s0, s4, 0xee00
	s_and_b32 s2, s0, 0xffff
	s_mul_i32 s2, s2, 0xba2f
	s_lshr_b32 s2, s2, 23
	s_mul_i32 s3, s2, 0xb0
	s_sub_i32 s0, s0, s3
	s_lshl_b32 s3, s0, 5
	s_and_b32 s53, s3, 0xffe0
	s_and_b32 s0, s0, 0xffff
	s_cmpk_gt_u32 s0, 0x57
	s_cselect_b32 s55, 0xfffff500, 0
	s_cselect_b32 s54, 0x80, 0
	v_lshl_or_b32 v0, s2, 6, v34
	s_lshl_b32 s0, s53, 2
	v_lshl_add_u64 v[48:49], v[30:31], 0, s[0:1]
	v_mul_u32_u24_e32 v0, 0x5800, v0
	v_lshl_add_u64 v[48:49], v[48:49], 0, v[0:1]
	v_add_co_u32_e32 v50, vcc, s20, v48
	s_add_i32 s55, s55, s53
	s_nop 0
	v_addc_co_u32_e32 v51, vcc, 0, v49, vcc
	v_add_co_u32_e32 v52, vcc, s18, v48
	s_lshl_b32 s0, s55, 1
	s_nop 0
	v_addc_co_u32_e32 v53, vcc, 0, v49, vcc
	v_add_co_u32_e32 v54, vcc, s21, v48
	s_and_b32 s3, s3, 0x60
	s_nop 0
	v_addc_co_u32_e32 v55, vcc, 0, v49, vcc
	v_add_co_u32_e32 v56, vcc, s19, v48
	s_and_b32 s0, s0, 0xffffff00
	s_nop 0
	v_addc_co_u32_e32 v57, vcc, 0, v49, vcc
	v_add_co_u32_e32 v58, vcc, s22, v48
	s_or_b32 s3, s3, s54
	s_nop 0
	v_addc_co_u32_e32 v59, vcc, 0, v49, vcc
	v_add_co_u32_e32 v60, vcc, s23, v48
	s_or_b32 s3, s3, s0
	s_nop 0
	v_addc_co_u32_e32 v61, vcc, 0, v49, vcc
	v_add_co_u32_e32 v62, vcc, s24, v48
	s_lshl_b32 s0, s2, 7
	s_nop 0
	v_addc_co_u32_e32 v63, vcc, 0, v49, vcc
	global_load_dword v0, v[48:49], off nt
	global_load_dword v66, v[50:51], off nt
	global_load_dword v67, v[52:53], off nt
	global_load_dword v68, v[54:55], off nt
	global_load_dword v69, v[56:57], off nt
	global_load_dword v70, v[58:59], off nt
	global_load_dword v71, v[60:61], off nt
	global_load_dword v72, v[62:63], off nt
	v_add_co_u32_e32 v50, vcc, s25, v48
	s_nop 1
	v_addc_co_u32_e32 v51, vcc, 0, v49, vcc
	v_add_co_u32_e32 v52, vcc, s26, v48
	s_nop 1
	v_addc_co_u32_e32 v53, vcc, 0, v49, vcc
	v_add_co_u32_e32 v54, vcc, s27, v48
	s_nop 1
	v_addc_co_u32_e32 v55, vcc, 0, v49, vcc
	v_add_co_u32_e32 v56, vcc, s28, v48
	s_nop 1
	v_addc_co_u32_e32 v57, vcc, 0, v49, vcc
	v_add_co_u32_e32 v58, vcc, s29, v48
	s_nop 1
	v_addc_co_u32_e32 v59, vcc, 0, v49, vcc
	v_add_co_u32_e32 v60, vcc, s30, v48
	s_nop 1
	v_addc_co_u32_e32 v61, vcc, 0, v49, vcc
	v_add_co_u32_e32 v62, vcc, s31, v48
	s_nop 1
	v_addc_co_u32_e32 v63, vcc, 0, v49, vcc
	v_add_co_u32_e32 v64, vcc, s34, v48
	s_nop 1
	v_addc_co_u32_e32 v65, vcc, 0, v49, vcc
	global_load_dword v73, v[50:51], off nt
	global_load_dword v74, v[52:53], off nt
	global_load_dword v75, v[54:55], off nt
	global_load_dword v76, v[56:57], off nt
	global_load_dword v77, v[58:59], off nt
	global_load_dword v78, v[60:61], off nt
	global_load_dword v79, v[62:63], off nt
	global_load_dword v80, v[64:65], off nt
	v_add_co_u32_e32 v50, vcc, s35, v48
	s_nop 1
	v_addc_co_u32_e32 v51, vcc, 0, v49, vcc
	v_add_co_u32_e32 v52, vcc, s36, v48
	s_nop 1
	v_addc_co_u32_e32 v53, vcc, 0, v49, vcc
	v_add_co_u32_e32 v54, vcc, s37, v48
	s_nop 1
	v_addc_co_u32_e32 v55, vcc, 0, v49, vcc
	v_add_co_u32_e32 v56, vcc, s38, v48
	s_nop 1
	v_addc_co_u32_e32 v57, vcc, 0, v49, vcc
	v_add_co_u32_e32 v58, vcc, s39, v48
	s_nop 1
	v_addc_co_u32_e32 v59, vcc, 0, v49, vcc
	v_add_co_u32_e32 v60, vcc, s40, v48
	s_nop 1
	v_addc_co_u32_e32 v61, vcc, 0, v49, vcc
	v_add_co_u32_e32 v62, vcc, s41, v48
	s_nop 1
	v_addc_co_u32_e32 v63, vcc, 0, v49, vcc
	v_add_co_u32_e32 v64, vcc, s42, v48
	s_nop 1
	v_addc_co_u32_e32 v65, vcc, 0, v49, vcc
	global_load_dword v81, v[50:51], off nt
	global_load_dword v82, v[52:53], off nt
	global_load_dword v83, v[54:55], off nt
	global_load_dword v84, v[56:57], off nt
	global_load_dword v85, v[58:59], off nt
	global_load_dword v86, v[60:61], off nt
	global_load_dword v87, v[62:63], off nt
	s_nop 0
	global_load_dword v64, v[64:65], off nt
	v_add_co_u32_e32 v50, vcc, s43, v48
	s_nop 1
	v_addc_co_u32_e32 v51, vcc, 0, v49, vcc
	v_add_co_u32_e32 v52, vcc, s44, v48
	s_nop 1
	v_addc_co_u32_e32 v53, vcc, 0, v49, vcc
	v_add_co_u32_e32 v54, vcc, s45, v48
	s_nop 1
	v_addc_co_u32_e32 v55, vcc, 0, v49, vcc
	v_add_co_u32_e32 v56, vcc, s46, v48
	s_nop 1
	v_addc_co_u32_e32 v57, vcc, 0, v49, vcc
	v_add_co_u32_e32 v58, vcc, s47, v48
	s_nop 1
	v_addc_co_u32_e32 v59, vcc, 0, v49, vcc
	v_add_co_u32_e32 v60, vcc, s48, v48
	s_nop 1
	v_addc_co_u32_e32 v61, vcc, 0, v49, vcc
	v_add_co_u32_e32 v62, vcc, s49, v48
	s_nop 1
	v_addc_co_u32_e32 v63, vcc, 0, v49, vcc
	v_add_co_u32_e32 v48, vcc, s51, v48
	s_nop 1
	v_addc_co_u32_e32 v49, vcc, 0, v49, vcc
	global_load_dword v50, v[50:51], off nt
	s_nop 0
	global_load_dword v51, v[52:53], off nt
	s_nop 0
	global_load_dword v52, v[54:55], off nt
	global_load_dword v53, v[56:57], off nt
	s_nop 0
	global_load_dword v54, v[58:59], off nt
	global_load_dword v55, v[60:61], off nt
	global_load_dword v56, v[62:63], off nt
	s_nop 0
	global_load_dword v48, v[48:49], off nt
	s_waitcnt vmcnt(30)
	ds_write2_b32 v39, v0, v66 offset1:66
	s_waitcnt vmcnt(28)
	ds_write2_b32 v39, v67, v68 offset0:132 offset1:198
	s_waitcnt vmcnt(26)
	ds_write2_b32 v40, v69, v70 offset0:8 offset1:74
	s_waitcnt vmcnt(24)
	ds_write2_b32 v40, v71, v72 offset0:140 offset1:206
	s_waitcnt vmcnt(22)
	ds_write2_b32 v41, v73, v74 offset0:16 offset1:82
	s_waitcnt vmcnt(20)
	ds_write2_b32 v41, v75, v76 offset0:148 offset1:214
	s_waitcnt vmcnt(18)
	ds_write2_b32 v42, v77, v78 offset0:24 offset1:90
	s_waitcnt vmcnt(16)
	ds_write2_b32 v42, v79, v80 offset0:156 offset1:222
	s_waitcnt vmcnt(14)
	ds_write2_b32 v43, v81, v82 offset0:32 offset1:98
	s_waitcnt vmcnt(12)
	ds_write2_b32 v43, v83, v84 offset0:164 offset1:230
	s_waitcnt vmcnt(10)
	ds_write2_b32 v44, v85, v86 offset0:40 offset1:106
	s_waitcnt vmcnt(8)
	ds_write2_b32 v44, v87, v64 offset0:172 offset1:238
	s_waitcnt vmcnt(6)
	ds_write2_b32 v45, v50, v51 offset0:48 offset1:114
	s_waitcnt vmcnt(4)
	ds_write2_b32 v45, v52, v53 offset0:180 offset1:246
	s_waitcnt vmcnt(2)
	ds_write2_b32 v46, v54, v55 offset0:56 offset1:122
	s_waitcnt vmcnt(0)
	ds_write2_b32 v46, v56, v48 offset0:188 offset1:254
	s_waitcnt lgkmcnt(0)
	ds_read2_b32 v[52:53], v47 offset0:33 offset1:41
	ds_read2_b32 v[54:55], v47 offset1:8
	ds_read2_b32 v[56:57], v47 offset0:66 offset1:74
	ds_read2_b32 v[58:59], v47 offset0:99 offset1:107
	ds_read2_b32 v[60:61], v47 offset0:132 offset1:140
	ds_read2_b32 v[62:63], v47 offset0:165 offset1:173
	ds_read2_b32 v[64:65], v47 offset0:198 offset1:206
	ds_read2_b32 v[66:67], v47 offset0:231 offset1:239
	v_or_b32_e32 v70, s3, v35
	v_ashrrev_i32_e32 v71, 31, v70
	v_lshl_add_u64 v[68:69], v[14:15], 0, s[0:1]
	v_lshlrev_b64 v[70:71], 11, v[70:71]
	s_waitcnt lgkmcnt(6)
	v_cvt_pk_bf16_f32 v48, v54, v52
	s_waitcnt lgkmcnt(4)
	v_cvt_pk_bf16_f32 v49, v56, v58
	s_waitcnt lgkmcnt(2)
	v_cvt_pk_bf16_f32 v50, v60, v62
	s_waitcnt lgkmcnt(0)
	v_cvt_pk_bf16_f32 v51, v64, v66
	v_lshl_add_u64 v[70:71], v[68:69], 0, v[70:71]
	v_or_b32_e32 v52, s3, v36
	global_store_dwordx4 v[70:71], v[48:51], off
	s_nop 1
	v_cvt_pk_bf16_f32 v48, v55, v53
	v_ashrrev_i32_e32 v53, 31, v52
	v_cvt_pk_bf16_f32 v49, v57, v59
	v_cvt_pk_bf16_f32 v50, v61, v63
	v_cvt_pk_bf16_f32 v51, v65, v67
	v_lshlrev_b64 v[52:53], 11, v[52:53]
	ds_read2_b32 v[54:55], v47 offset0:49 offset1:57
	ds_read2_b32 v[56:57], v47 offset0:16 offset1:24
	ds_read2_b32 v[58:59], v47 offset0:82 offset1:90
	ds_read2_b32 v[60:61], v47 offset0:115 offset1:123
	ds_read2_b32 v[62:63], v47 offset0:148 offset1:156
	ds_read2_b32 v[64:65], v47 offset0:181 offset1:189
	ds_read2_b32 v[66:67], v47 offset0:214 offset1:222
	ds_read2_b32 v[70:71], v47 offset0:247 offset1:255
	v_lshl_add_u64 v[52:53], v[68:69], 0, v[52:53]
	global_store_dwordx4 v[52:53], v[48:51], off
	v_or_b32_e32 v52, s3, v37
	v_ashrrev_i32_e32 v53, 31, v52
	v_lshlrev_b64 v[52:53], 11, v[52:53]
	s_waitcnt lgkmcnt(6)
	v_cvt_pk_bf16_f32 v48, v56, v54
	s_waitcnt lgkmcnt(4)
	v_cvt_pk_bf16_f32 v49, v58, v60
	s_waitcnt lgkmcnt(2)
	v_cvt_pk_bf16_f32 v50, v62, v64
	s_waitcnt lgkmcnt(0)
	v_cvt_pk_bf16_f32 v51, v66, v70
	v_lshl_add_u64 v[52:53], v[68:69], 0, v[52:53]
	global_store_dwordx4 v[52:53], v[48:51], off
	v_or_b32_e32 v52, s3, v38
	v_ashrrev_i32_e32 v53, 31, v52
	v_lshlrev_b64 v[52:53], 11, v[52:53]
	v_cvt_pk_bf16_f32 v48, v57, v55
	v_cvt_pk_bf16_f32 v49, v59, v61
	v_cvt_pk_bf16_f32 v50, v63, v65
	v_cvt_pk_bf16_f32 v51, v67, v71
	v_lshl_add_u64 v[52:53], v[68:69], 0, v[52:53]
	global_store_dwordx4 v[52:53], v[48:51], off
	s_waitcnt lgkmcnt(0)

.LBB0_57:
	s_andn2_b64 vcc, exec, s[2:3]
	s_cbranch_vccnz .LBB0_30
	s_mul_hi_i32 s0, s4, 0x38e38e39
	s_lshr_b32 s2, s0, 31
	s_ashr_i32 s0, s0, 6
	s_add_i32 s2, s0, s2
	s_mul_i32 s0, s2, 0xfffffee0
	s_add_i32 s0, s4, s0
	s_mul_i32 s3, s2, 0xffffdc00
	s_add_i32 s54, s8, s3
	s_ashr_i32 s0, s0, 5
	s_add_i32 s3, s0, -1
	s_lshl_b32 s0, s0, 7
	s_and_b32 s55, s54, 0x60
	s_and_b32 s53, s14, 0x700
	s_or_b32 s0, s0, s55
	s_add_i32 s0, s0, s53
	s_addk_i32 s0, 0x380
	s_cmp_lt_u32 s3, 2
	s_cselect_b32 s0, s0, s54
	s_lshl_b32 s2, s2, 6
	v_or_b32_e32 v0, s2, v34
	s_ashr_i32 s55, s54, 31
	v_lshl_add_u64 v[48:49], s[54:55], 2, v[32:33]
	v_or_b32_e32 v52, 2, v0
	v_or_b32_e32 v54, 4, v0
	v_or_b32_e32 v56, 6, v0
	v_or_b32_e32 v58, 8, v0
	v_or_b32_e32 v60, 10, v0
	v_or_b32_e32 v62, 12, v0
	v_or_b32_e32 v64, 14, v0
	v_mad_i64_i32 v[50:51], s[54:55], v0, s52, v[48:49]
	v_mad_i64_i32 v[52:53], s[54:55], v52, s52, v[48:49]
	v_mad_i64_i32 v[54:55], s[54:55], v54, s52, v[48:49]
	v_mad_i64_i32 v[56:57], s[54:55], v56, s52, v[48:49]
	v_mad_i64_i32 v[58:59], s[54:55], v58, s52, v[48:49]
	v_mad_i64_i32 v[60:61], s[54:55], v60, s52, v[48:49]
	v_mad_i64_i32 v[62:63], s[54:55], v62, s52, v[48:49]
	v_mad_i64_i32 v[64:65], s[54:55], v64, s52, v[48:49]
	global_load_dword v66, v[50:51], off nt
	global_load_dword v67, v[52:53], off nt
	global_load_dword v68, v[54:55], off nt
	global_load_dword v69, v[56:57], off nt
	global_load_dword v70, v[58:59], off nt
	global_load_dword v71, v[60:61], off nt
	global_load_dword v72, v[62:63], off nt
	global_load_dword v73, v[64:65], off nt
	v_or_b32_e32 v50, 16, v0
	v_or_b32_e32 v52, 18, v0
	v_or_b32_e32 v54, 20, v0
	v_or_b32_e32 v56, 22, v0
	v_or_b32_e32 v58, 24, v0
	v_or_b32_e32 v60, 26, v0
	v_or_b32_e32 v62, 28, v0
	v_or_b32_e32 v64, 30, v0
	v_mad_i64_i32 v[50:51], s[54:55], v50, s52, v[48:49]
	v_mad_i64_i32 v[52:53], s[54:55], v52, s52, v[48:49]
	v_mad_i64_i32 v[54:55], s[54:55], v54, s52, v[48:49]
	v_mad_i64_i32 v[56:57], s[54:55], v56, s52, v[48:49]
	v_mad_i64_i32 v[58:59], s[54:55], v58, s52, v[48:49]
	v_mad_i64_i32 v[60:61], s[54:55], v60, s52, v[48:49]
	v_mad_i64_i32 v[62:63], s[54:55], v62, s52, v[48:49]
	v_mad_i64_i32 v[64:65], s[54:55], v64, s52, v[48:49]
	global_load_dword v74, v[50:51], off nt
	global_load_dword v75, v[52:53], off nt
	global_load_dword v76, v[54:55], off nt
	global_load_dword v77, v[56:57], off nt
	global_load_dword v78, v[58:59], off nt
	global_load_dword v79, v[60:61], off nt
	global_load_dword v80, v[62:63], off nt
	global_load_dword v81, v[64:65], off nt
	v_or_b32_e32 v50, 32, v0
	v_or_b32_e32 v52, 34, v0
	v_or_b32_e32 v54, 36, v0
	v_or_b32_e32 v56, 38, v0
	v_or_b32_e32 v58, 40, v0
	v_or_b32_e32 v60, 42, v0
	v_or_b32_e32 v62, 44, v0
	v_or_b32_e32 v64, 46, v0
	v_mad_i64_i32 v[50:51], s[54:55], v50, s52, v[48:49]
	v_mad_i64_i32 v[52:53], s[54:55], v52, s52, v[48:49]
	v_mad_i64_i32 v[54:55], s[54:55], v54, s52, v[48:49]
	v_mad_i64_i32 v[56:57], s[54:55], v56, s52, v[48:49]
	v_mad_i64_i32 v[58:59], s[54:55], v58, s52, v[48:49]
	v_mad_i64_i32 v[60:61], s[54:55], v60, s52, v[48:49]
	v_mad_i64_i32 v[62:63], s[54:55], v62, s52, v[48:49]
	v_mad_i64_i32 v[64:65], s[54:55], v64, s52, v[48:49]
	global_load_dword v82, v[50:51], off nt
	global_load_dword v83, v[52:53], off nt
	global_load_dword v84, v[54:55], off nt
	global_load_dword v85, v[56:57], off nt
	global_load_dword v86, v[58:59], off nt
	global_load_dword v87, v[60:61], off nt
	global_load_dword v88, v[62:63], off nt
	s_nop 0
	global_load_dword v64, v[64:65], off nt
	v_or_b32_e32 v50, 48, v0
	v_or_b32_e32 v52, 50, v0
	v_or_b32_e32 v54, 52, v0
	v_or_b32_e32 v56, 54, v0
	v_or_b32_e32 v58, 56, v0
	v_or_b32_e32 v60, 58, v0
	v_or_b32_e32 v62, 60, v0
	v_or_b32_e32 v0, 62, v0
	v_mad_i64_i32 v[50:51], s[54:55], v50, s52, v[48:49]
	v_mad_i64_i32 v[52:53], s[54:55], v52, s52, v[48:49]
	v_mad_i64_i32 v[54:55], s[54:55], v54, s52, v[48:49]
	v_mad_i64_i32 v[56:57], s[54:55], v56, s52, v[48:49]
	v_mad_i64_i32 v[58:59], s[54:55], v58, s52, v[48:49]
	v_mad_i64_i32 v[60:61], s[54:55], v60, s52, v[48:49]
	v_mad_i64_i32 v[62:63], s[54:55], v62, s52, v[48:49]
	v_mad_i64_i32 v[48:49], s[54:55], v0, s52, v[48:49]
	global_load_dword v0, v[50:51], off nt
	s_nop 0
	global_load_dword v50, v[52:53], off nt
	global_load_dword v51, v[54:55], off nt
	s_nop 0
	global_load_dword v52, v[56:57], off nt
	global_load_dword v53, v[58:59], off nt
	global_load_dword v54, v[60:61], off nt
	global_load_dword v55, v[62:63], off nt
	s_nop 0
	global_load_dword v48, v[48:49], off nt
	s_waitcnt vmcnt(30)
	ds_write2_b32 v39, v66, v67 offset1:66
	s_waitcnt vmcnt(28)
	ds_write2_b32 v39, v68, v69 offset0:132 offset1:198
	s_waitcnt vmcnt(26)
	ds_write2_b32 v40, v70, v71 offset0:8 offset1:74
	s_waitcnt vmcnt(24)
	ds_write2_b32 v40, v72, v73 offset0:140 offset1:206
	s_waitcnt vmcnt(22)
	ds_write2_b32 v41, v74, v75 offset0:16 offset1:82
	s_waitcnt vmcnt(20)
	ds_write2_b32 v41, v76, v77 offset0:148 offset1:214
	s_waitcnt vmcnt(18)
	ds_write2_b32 v42, v78, v79 offset0:24 offset1:90
	s_waitcnt vmcnt(16)
	ds_write2_b32 v42, v80, v81 offset0:156 offset1:222
	s_waitcnt vmcnt(14)
	ds_write2_b32 v43, v82, v83 offset0:32 offset1:98
	s_waitcnt vmcnt(12)
	ds_write2_b32 v43, v84, v85 offset0:164 offset1:230
	s_waitcnt vmcnt(10)
	ds_write2_b32 v44, v86, v87 offset0:40 offset1:106
	s_waitcnt vmcnt(8)
	ds_write2_b32 v44, v88, v64 offset0:172 offset1:238
	s_waitcnt vmcnt(6)
	ds_write2_b32 v45, v0, v50 offset0:48 offset1:114
	s_waitcnt vmcnt(4)
	ds_write2_b32 v45, v51, v52 offset0:180 offset1:246
	s_waitcnt vmcnt(2)
	ds_write2_b32 v46, v53, v54 offset0:56 offset1:122
	s_waitcnt vmcnt(0)
	ds_write2_b32 v46, v55, v48 offset0:188 offset1:254
	s_waitcnt lgkmcnt(0)
	ds_read2_b32 v[52:53], v47 offset0:33 offset1:41
	ds_read2_b32 v[54:55], v47 offset1:8
	ds_read2_b32 v[56:57], v47 offset0:66 offset1:74
	ds_read2_b32 v[58:59], v47 offset0:99 offset1:107
	ds_read2_b32 v[60:61], v47 offset0:132 offset1:140
	ds_read2_b32 v[62:63], v47 offset0:165 offset1:173
	ds_read2_b32 v[64:65], v47 offset0:198 offset1:206
	ds_read2_b32 v[66:67], v47 offset0:231 offset1:239
	v_or_b32_e32 v70, s0, v35
	s_ashr_i32 s3, s2, 31
	v_ashrrev_i32_e32 v71, 31, v70
	v_lshl_add_u64 v[68:69], s[2:3], 1, v[16:17]
	v_lshlrev_b64 v[70:71], 11, v[70:71]
	s_waitcnt lgkmcnt(6)
	v_cvt_pk_bf16_f32 v48, v54, v52
	s_waitcnt lgkmcnt(4)
	v_cvt_pk_bf16_f32 v49, v56, v58
	s_waitcnt lgkmcnt(2)
	v_cvt_pk_bf16_f32 v50, v60, v62
	s_waitcnt lgkmcnt(0)
	v_cvt_pk_bf16_f32 v51, v64, v66
	v_lshl_add_u64 v[70:71], v[68:69], 0, v[70:71]
	v_or_b32_e32 v52, s0, v36
	global_store_dwordx4 v[70:71], v[48:51], off
	s_nop 1
	v_cvt_pk_bf16_f32 v48, v55, v53
	v_ashrrev_i32_e32 v53, 31, v52
	v_cvt_pk_bf16_f32 v49, v57, v59
	v_cvt_pk_bf16_f32 v50, v61, v63
	v_cvt_pk_bf16_f32 v51, v65, v67
	v_lshlrev_b64 v[52:53], 11, v[52:53]
	ds_read2_b32 v[54:55], v47 offset0:49 offset1:57
	ds_read2_b32 v[56:57], v47 offset0:16 offset1:24
	ds_read2_b32 v[58:59], v47 offset0:82 offset1:90
	ds_read2_b32 v[60:61], v47 offset0:115 offset1:123
	ds_read2_b32 v[62:63], v47 offset0:148 offset1:156
	ds_read2_b32 v[64:65], v47 offset0:181 offset1:189
	ds_read2_b32 v[66:67], v47 offset0:214 offset1:222
	ds_read2_b32 v[70:71], v47 offset0:247 offset1:255
	v_lshl_add_u64 v[52:53], v[68:69], 0, v[52:53]
	global_store_dwordx4 v[52:53], v[48:51], off
	v_or_b32_e32 v52, s0, v37
	v_ashrrev_i32_e32 v53, 31, v52
	v_lshlrev_b64 v[52:53], 11, v[52:53]
	s_waitcnt lgkmcnt(6)
	v_cvt_pk_bf16_f32 v48, v56, v54
	s_waitcnt lgkmcnt(4)
	v_cvt_pk_bf16_f32 v49, v58, v60
	s_waitcnt lgkmcnt(2)
	v_cvt_pk_bf16_f32 v50, v62, v64
	s_waitcnt lgkmcnt(0)
	v_cvt_pk_bf16_f32 v51, v66, v70
	v_lshl_add_u64 v[52:53], v[68:69], 0, v[52:53]
	global_store_dwordx4 v[52:53], v[48:51], off
	v_or_b32_e32 v52, s0, v38
	v_ashrrev_i32_e32 v53, 31, v52
	v_lshlrev_b64 v[52:53], 11, v[52:53]
	v_cvt_pk_bf16_f32 v48, v57, v55
	v_cvt_pk_bf16_f32 v49, v59, v61
	v_cvt_pk_bf16_f32 v50, v63, v65
	v_cvt_pk_bf16_f32 v51, v67, v71
	v_lshl_add_u64 v[52:53], v[68:69], 0, v[52:53]
	global_store_dwordx4 v[52:53], v[48:51], off
	s_waitcnt lgkmcnt(0)
	s_branch .LBB0_30
